# FFN-out and out-proj residual epilogues: per-load progressive vmcnt waits instead of one vmcnt(0) before the first row group
# baseline (speedup 1.0000x reference)
.LBB0_274:
	v_mbcnt_lo_u32_b32 v94, -1, 0
	v_mbcnt_hi_u32_b32 v94, -1, v94
	s_lshl_b32 s9, s25, 8
	v_ashrrev_i32_e32 v95, 1, v94
	s_lshl_b32 s7, s26, 8
	s_or_b32 s9, s9, s59
	v_and_b32_e32 v95, -8, v95
	s_add_i32 s7, s7, s58
	v_add_u32_e32 v204, s9, v95
	v_ashrrev_i32_e32 v205, 31, v204
	v_and_or_b32 v234, v94, 15, s7
	v_lshlrev_b64 v[236:237], 1, v[204:205]
	v_ashrrev_i32_e32 v235, 31, v234
	v_lshlrev_b32_e32 v244, 2, v94
	v_cmp_gt_u32_e32 vcc, 16, v94
	v_lshl_add_u64 v[94:95], s[42:43], 0, v[236:237]
	v_lshlrev_b64 v[238:239], 11, v[234:235]
	v_lshl_add_u64 v[96:97], v[94:95], 0, v[238:239]
	global_load_dwordx4 v[190:193], v[96:97], off
	global_load_dwordx4 v[186:189], v[96:97], off offset:256
	v_or_b32_e32 v230, 16, v234
	v_ashrrev_i32_e32 v231, 31, v230
	v_or_b32_e32 v210, 32, v234
	v_lshlrev_b64 v[232:233], 11, v[230:231]
	v_ashrrev_i32_e32 v211, 31, v210
	v_or_b32_e32 v226, 48, v234
	v_lshl_add_u64 v[96:97], v[94:95], 0, v[232:233]
	v_lshlrev_b64 v[212:213], 11, v[210:211]
	v_ashrrev_i32_e32 v227, 31, v226
	v_add_u32_e32 v222, 0x80, v234
	global_load_dwordx4 v[182:185], v[96:97], off
	global_load_dwordx4 v[178:181], v[96:97], off offset:256
	v_lshl_add_u64 v[96:97], v[94:95], 0, v[212:213]
	v_lshlrev_b64 v[228:229], 11, v[226:227]
	v_ashrrev_i32_e32 v223, 31, v222
	v_add_u32_e32 v218, 0x90, v234
	global_load_dwordx4 v[174:177], v[96:97], off
	global_load_dwordx4 v[170:173], v[96:97], off offset:256
	v_lshl_add_u64 v[96:97], v[94:95], 0, v[228:229]
	v_lshlrev_b64 v[224:225], 11, v[222:223]
	v_ashrrev_i32_e32 v219, 31, v218
	v_add_u32_e32 v214, 0xa0, v234
	v_add_u32_e32 v206, 0xb0, v234
	global_load_dwordx4 v[166:169], v[96:97], off
	global_load_dwordx4 v[162:165], v[96:97], off offset:256
	v_lshl_add_u64 v[96:97], v[94:95], 0, v[224:225]
	v_lshlrev_b64 v[220:221], 11, v[218:219]
	v_ashrrev_i32_e32 v215, 31, v214
	v_ashrrev_i32_e32 v207, 31, v206
	global_load_dwordx4 v[158:161], v[96:97], off
	global_load_dwordx4 v[150:153], v[96:97], off offset:256
	v_lshl_add_u64 v[96:97], v[94:95], 0, v[220:221]
	v_lshlrev_b64 v[216:217], 11, v[214:215]
	v_lshlrev_b64 v[208:209], 11, v[206:207]
	global_load_dwordx4 v[142:145], v[96:97], off
	global_load_dwordx4 v[138:141], v[96:97], off offset:256
	v_lshl_add_u64 v[96:97], v[94:95], 0, v[216:217]
	v_lshl_add_u64 v[94:95], v[94:95], 0, v[208:209]
	global_load_dwordx4 v[126:129], v[96:97], off
	global_load_dwordx4 v[114:117], v[96:97], off offset:256
	global_load_dwordx4 v[106:109], v[94:95], off
	s_nop 0
	global_load_dwordx4 v[94:97], v[94:95], off offset:256
	v_xor_b32_e32 v245, 64, v244
	v_xor_b32_e32 v244, 0x80, v244
	s_lshl_b32 s82, s25, 2
	s_ashr_i32 s83, s82, 31
	s_waitcnt vmcnt(15)
	v_lshlrev_b32_e32 v246, 16, v190
	v_and_b32_e32 v247, 0xffff0000, v190
	v_lshlrev_b32_e32 v190, 16, v191
	v_and_b32_e32 v191, 0xffff0000, v191
	v_pk_fma_f32 v[156:157], v[156:157], 0.5, v[190:191] op_sel_hi:[1,0,1]
	v_lshlrev_b32_e32 v190, 16, v192
	v_and_b32_e32 v191, 0xffff0000, v192
	v_pk_fma_f32 v[146:147], v[146:147], 0.5, v[190:191] op_sel_hi:[1,0,1]
	v_pk_fma_f32 v[154:155], v[154:155], 0.5, v[246:247] op_sel_hi:[1,0,1]
	v_pk_add_f32 v[190:191], v[146:147], 0 op_sel_hi:[1,0]
	v_lshlrev_b32_e32 v146, 16, v193
	v_and_b32_e32 v147, 0xffff0000, v193
	v_pk_add_f32 v[154:155], v[154:155], 0 op_sel_hi:[1,0]
	v_pk_fma_f32 v[146:147], v[148:149], 0.5, v[146:147] op_sel_hi:[1,0,1]
	v_pk_add_f32 v[156:157], v[156:157], 0 op_sel_hi:[1,0]
	v_pk_add_f32 v[192:193], v[146:147], 0 op_sel_hi:[1,0]
	v_cvt_pk_bf16_f32 v146, v154, v155
	v_lshl_add_u64 v[154:155], s[88:89], 0, v[238:239]
	v_cvt_pk_bf16_f32 v147, v156, v157
	v_cvt_pk_bf16_f32 v148, v190, v191
	v_cvt_pk_bf16_f32 v149, v192, v193
	v_lshl_add_u64 v[154:155], v[154:155], 0, v[236:237]
	global_store_dwordx4 v[154:155], v[146:149], off
	v_lshlrev_b32_e32 v156, 16, v146
	v_lshlrev_b32_e32 v157, 16, v147
	v_and_b32_e32 v146, 0xffff0000, v146
	v_and_b32_e32 v147, 0xffff0000, v147
	v_mul_f32_e32 v146, v146, v146
	v_mul_f32_e32 v147, v147, v147
	v_lshlrev_b32_e32 v190, 16, v148
	v_and_b32_e32 v148, 0xffff0000, v148
	v_fmac_f32_e32 v146, v156, v156
	v_fmac_f32_e32 v147, v157, v157
	v_add_f32_e32 v146, v146, v147
	v_mul_f32_e32 v147, v148, v148
	v_lshlrev_b32_e32 v191, 16, v149
	v_and_b32_e32 v149, 0xffff0000, v149
	v_fmac_f32_e32 v147, v190, v190
	v_add_f32_e32 v146, v147, v146
	v_mul_f32_e32 v147, v149, v149
	v_fmac_f32_e32 v147, v191, v191
	v_add_f32_e32 v156, v147, v146
	s_waitcnt vmcnt(15)
	v_lshlrev_b32_e32 v146, 16, v186
	v_and_b32_e32 v147, 0xffff0000, v186
	v_pk_fma_f32 v[134:135], v[134:135], 0.5, v[146:147] op_sel_hi:[1,0,1]
	v_lshlrev_b32_e32 v146, 16, v187
	v_and_b32_e32 v147, 0xffff0000, v187
	v_pk_fma_f32 v[136:137], v[136:137], 0.5, v[146:147] op_sel_hi:[1,0,1]
	v_lshlrev_b32_e32 v146, 16, v188
	v_and_b32_e32 v147, 0xffff0000, v188
	v_pk_fma_f32 v[130:131], v[130:131], 0.5, v[146:147] op_sel_hi:[1,0,1]
	v_pk_add_f32 v[134:135], v[134:135], 0 op_sel_hi:[1,0]
	v_pk_add_f32 v[146:147], v[130:131], 0 op_sel_hi:[1,0]
	v_lshlrev_b32_e32 v130, 16, v189
	v_and_b32_e32 v131, 0xffff0000, v189
	v_pk_fma_f32 v[130:131], v[132:133], 0.5, v[130:131] op_sel_hi:[1,0,1]
	v_pk_add_f32 v[136:137], v[136:137], 0 op_sel_hi:[1,0]
	v_pk_add_f32 v[148:149], v[130:131], 0 op_sel_hi:[1,0]
	v_cvt_pk_bf16_f32 v130, v134, v135
	v_cvt_pk_bf16_f32 v131, v136, v137
	v_cvt_pk_bf16_f32 v132, v146, v147
	v_cvt_pk_bf16_f32 v133, v148, v149
	global_store_dwordx4 v[154:155], v[130:133], off offset:256
	v_lshlrev_b32_e32 v134, 16, v130
	v_lshlrev_b32_e32 v135, 16, v131
	v_and_b32_e32 v130, 0xffff0000, v130
	v_and_b32_e32 v131, 0xffff0000, v131
	v_mul_f32_e32 v130, v130, v130
	v_fmac_f32_e32 v130, v134, v134
	v_mul_f32_e32 v131, v131, v131
	v_lshlrev_b32_e32 v136, 16, v132
	v_and_b32_e32 v132, 0xffff0000, v132
	v_add_f32_e32 v130, v130, v156
	v_fmac_f32_e32 v131, v135, v135
	v_add_f32_e32 v130, v131, v130
	v_mul_f32_e32 v131, v132, v132
	v_lshlrev_b32_e32 v137, 16, v133
	v_and_b32_e32 v133, 0xffff0000, v133
	v_fmac_f32_e32 v131, v136, v136
	v_add_f32_e32 v130, v131, v130
	v_mul_f32_e32 v131, v133, v133
	v_fmac_f32_e32 v131, v137, v137
	v_add_f32_e32 v130, v131, v130
	ds_bpermute_b32 v131, v245, v130
	s_waitcnt lgkmcnt(0)
	v_add_f32_e32 v130, v130, v131
	ds_bpermute_b32 v131, v244, v130
	s_and_saveexec_b64 s[48:49], vcc
	s_mov_b32 s31, 0xf800000
	s_cbranch_execz .LBB0_276
	v_lshlrev_b64 v[132:133], 6, v[234:235]
	v_lshl_add_u64 v[132:133], s[38:39], 0, v[132:133]
	v_lshl_add_u64 v[132:133], s[82:83], 2, v[132:133]
	s_lshl_b32 s76, s55, 2
	v_lshl_add_u64 v[132:133], v[132:133], 0, s[76:77]
	s_waitcnt lgkmcnt(0)
	v_add_f32_e32 v130, v130, v131
	global_store_dword v[132:133], v130, off
.LBB0_276:
	s_or_b64 exec, exec, s[48:49]
	s_waitcnt vmcnt(16)
	v_lshlrev_b32_e32 v130, 16, v182
	s_waitcnt lgkmcnt(0)
	v_and_b32_e32 v131, 0xffff0000, v182
	v_pk_fma_f32 v[122:123], v[122:123], 0.5, v[130:131] op_sel_hi:[1,0,1]
	v_lshlrev_b32_e32 v130, 16, v183
	v_and_b32_e32 v131, 0xffff0000, v183
	v_pk_fma_f32 v[124:125], v[124:125], 0.5, v[130:131] op_sel_hi:[1,0,1]
	v_lshlrev_b32_e32 v130, 16, v184
	v_and_b32_e32 v131, 0xffff0000, v184
	v_pk_fma_f32 v[118:119], v[118:119], 0.5, v[130:131] op_sel_hi:[1,0,1]
	v_pk_add_f32 v[122:123], v[122:123], 0 op_sel_hi:[1,0]
	v_pk_add_f32 v[130:131], v[118:119], 0 op_sel_hi:[1,0]
	v_lshlrev_b32_e32 v118, 16, v185
	v_and_b32_e32 v119, 0xffff0000, v185
	v_pk_fma_f32 v[118:119], v[120:121], 0.5, v[118:119] op_sel_hi:[1,0,1]
	v_pk_add_f32 v[124:125], v[124:125], 0 op_sel_hi:[1,0]
	v_pk_add_f32 v[132:133], v[118:119], 0 op_sel_hi:[1,0]
	v_cvt_pk_bf16_f32 v118, v122, v123
	v_cvt_pk_bf16_f32 v119, v124, v125
	v_and_b32_e32 v123, 0xffff0000, v118
	v_lshlrev_b32_e32 v122, 16, v118
	v_and_b32_e32 v125, 0xffff0000, v119
	v_mul_f32_e32 v123, v123, v123
	v_cvt_pk_bf16_f32 v120, v130, v131
	v_lshlrev_b32_e32 v124, 16, v119
	v_fmac_f32_e32 v123, v122, v122
	v_mul_f32_e32 v122, v125, v125
	v_and_b32_e32 v131, 0xffff0000, v120
	v_fmac_f32_e32 v122, v124, v124
	v_cvt_pk_bf16_f32 v121, v132, v133
	v_lshlrev_b32_e32 v130, 16, v120
	v_add_f32_e32 v122, v123, v122
	v_mul_f32_e32 v123, v131, v131
	v_and_b32_e32 v133, 0xffff0000, v121
	v_fmac_f32_e32 v123, v130, v130
	v_lshlrev_b32_e32 v132, 16, v121
	v_add_f32_e32 v122, v123, v122
	v_mul_f32_e32 v123, v133, v133
	v_fmac_f32_e32 v123, v132, v132
	v_add_f32_e32 v124, v123, v122
	s_waitcnt vmcnt(15)
	v_lshlrev_b32_e32 v122, 16, v178
	v_and_b32_e32 v123, 0xffff0000, v178
	v_pk_fma_f32 v[110:111], v[110:111], 0.5, v[122:123] op_sel_hi:[1,0,1]
	v_lshlrev_b32_e32 v122, 16, v179
	v_and_b32_e32 v123, 0xffff0000, v179
	v_pk_fma_f32 v[112:113], v[112:113], 0.5, v[122:123] op_sel_hi:[1,0,1]
	v_lshlrev_b32_e32 v122, 16, v180
	v_and_b32_e32 v123, 0xffff0000, v180
	v_pk_add_f32 v[110:111], v[110:111], 0 op_sel_hi:[1,0]
	v_pk_fma_f32 v[102:103], v[102:103], 0.5, v[122:123] op_sel_hi:[1,0,1]
	v_pk_add_f32 v[112:113], v[112:113], 0 op_sel_hi:[1,0]
	v_pk_add_f32 v[102:103], v[102:103], 0 op_sel_hi:[1,0]
	v_lshlrev_b32_e32 v122, 16, v181
	v_and_b32_e32 v123, 0xffff0000, v181
	v_cvt_pk_bf16_f32 v110, v110, v111
	v_pk_fma_f32 v[104:105], v[104:105], 0.5, v[122:123] op_sel_hi:[1,0,1]
	v_cvt_pk_bf16_f32 v111, v112, v113
	v_cvt_pk_bf16_f32 v112, v102, v103
	v_and_b32_e32 v103, 0xffff0000, v110
	v_pk_add_f32 v[104:105], v[104:105], 0 op_sel_hi:[1,0]
	v_lshlrev_b32_e32 v102, 16, v110
	v_mul_f32_e32 v103, v103, v103
	v_cvt_pk_bf16_f32 v113, v104, v105
	v_and_b32_e32 v105, 0xffff0000, v111
	v_fmac_f32_e32 v103, v102, v102
	v_lshlrev_b32_e32 v104, 16, v111
	v_add_f32_e32 v102, v103, v124
	v_mul_f32_e32 v103, v105, v105
	v_and_b32_e32 v123, 0xffff0000, v112
	v_fmac_f32_e32 v103, v104, v104
	v_lshlrev_b32_e32 v122, 16, v112
	v_add_f32_e32 v102, v103, v102
	v_mul_f32_e32 v103, v123, v123
	v_and_b32_e32 v130, 0xffff0000, v113
	v_fmac_f32_e32 v103, v122, v122
	v_lshlrev_b32_e32 v125, 16, v113
	v_add_f32_e32 v102, v103, v102
	v_mul_f32_e32 v103, v130, v130
	v_fmac_f32_e32 v103, v125, v125
	v_add_f32_e32 v102, v103, v102
	ds_bpermute_b32 v103, v245, v102
	v_lshl_add_u64 v[104:105], s[88:89], 0, v[232:233]
	v_lshl_add_u64 v[104:105], v[204:205], 1, v[104:105]
	global_store_dwordx4 v[104:105], v[118:121], off
	global_store_dwordx4 v[104:105], v[110:113], off offset:256
	s_waitcnt lgkmcnt(0)
	v_add_f32_e32 v102, v102, v103
	ds_bpermute_b32 v103, v244, v102
	s_and_saveexec_b64 s[48:49], vcc
	s_cbranch_execz .LBB0_278
	v_lshlrev_b64 v[104:105], 6, v[230:231]
	v_lshl_add_u64 v[104:105], s[38:39], 0, v[104:105]
	v_lshl_add_u64 v[104:105], s[82:83], 2, v[104:105]
	s_lshl_b32 s76, s55, 2
	v_lshl_add_u64 v[104:105], v[104:105], 0, s[76:77]
	s_waitcnt lgkmcnt(0)
	v_add_f32_e32 v102, v102, v103
	global_store_dword v[104:105], v102, off
.LBB0_278:
	s_or_b64 exec, exec, s[48:49]
	s_waitcnt vmcnt(17)
	v_lshlrev_b32_e32 v102, 16, v174
	s_waitcnt lgkmcnt(0)
	v_and_b32_e32 v103, 0xffff0000, v174
	v_pk_fma_f32 v[98:99], v[98:99], 0.5, v[102:103] op_sel_hi:[1,0,1]
	v_lshlrev_b32_e32 v102, 16, v175
	v_and_b32_e32 v103, 0xffff0000, v175
	v_pk_fma_f32 v[100:101], v[100:101], 0.5, v[102:103] op_sel_hi:[1,0,1]
	v_lshlrev_b32_e32 v102, 16, v176
	v_and_b32_e32 v103, 0xffff0000, v176
	v_pk_fma_f32 v[90:91], v[90:91], 0.5, v[102:103] op_sel_hi:[1,0,1]
	v_pk_add_f32 v[98:99], v[98:99], 0 op_sel_hi:[1,0]
	v_pk_add_f32 v[102:103], v[90:91], 0 op_sel_hi:[1,0]
	v_lshlrev_b32_e32 v90, 16, v177
	v_and_b32_e32 v91, 0xffff0000, v177
	v_pk_fma_f32 v[90:91], v[92:93], 0.5, v[90:91] op_sel_hi:[1,0,1]
	v_pk_add_f32 v[100:101], v[100:101], 0 op_sel_hi:[1,0]
	v_pk_add_f32 v[104:105], v[90:91], 0 op_sel_hi:[1,0]
	v_cvt_pk_bf16_f32 v90, v98, v99
	v_cvt_pk_bf16_f32 v91, v100, v101
	v_and_b32_e32 v99, 0xffff0000, v90
	v_lshlrev_b32_e32 v98, 16, v90
	v_and_b32_e32 v101, 0xffff0000, v91
	v_mul_f32_e32 v99, v99, v99
	v_cvt_pk_bf16_f32 v92, v102, v103
	v_lshlrev_b32_e32 v100, 16, v91
	v_fmac_f32_e32 v99, v98, v98
	v_mul_f32_e32 v98, v101, v101
	v_and_b32_e32 v103, 0xffff0000, v92
	v_fmac_f32_e32 v98, v100, v100
	v_cvt_pk_bf16_f32 v93, v104, v105
	v_lshlrev_b32_e32 v102, 16, v92
	v_add_f32_e32 v98, v99, v98
	v_mul_f32_e32 v99, v103, v103
	v_and_b32_e32 v105, 0xffff0000, v93
	v_fmac_f32_e32 v99, v102, v102
	v_lshlrev_b32_e32 v104, 16, v93
	v_add_f32_e32 v98, v99, v98
	v_mul_f32_e32 v99, v105, v105
	v_fmac_f32_e32 v99, v104, v104
	v_add_f32_e32 v100, v99, v98
	s_waitcnt vmcnt(16)
	v_lshlrev_b32_e32 v98, 16, v170
	v_and_b32_e32 v99, 0xffff0000, v170
	v_pk_fma_f32 v[86:87], v[86:87], 0.5, v[98:99] op_sel_hi:[1,0,1]
	v_lshlrev_b32_e32 v98, 16, v171
	v_and_b32_e32 v99, 0xffff0000, v171
	v_pk_fma_f32 v[88:89], v[88:89], 0.5, v[98:99] op_sel_hi:[1,0,1]
	v_lshlrev_b32_e32 v98, 16, v172
	v_and_b32_e32 v99, 0xffff0000, v172
	v_pk_fma_f32 v[82:83], v[82:83], 0.5, v[98:99] op_sel_hi:[1,0,1]
	v_lshlrev_b32_e32 v98, 16, v173
	v_and_b32_e32 v99, 0xffff0000, v173
	v_pk_add_f32 v[86:87], v[86:87], 0 op_sel_hi:[1,0]
	v_pk_fma_f32 v[84:85], v[84:85], 0.5, v[98:99] op_sel_hi:[1,0,1]
	v_pk_add_f32 v[82:83], v[82:83], 0 op_sel_hi:[1,0]
	v_pk_add_f32 v[98:99], v[84:85], 0 op_sel_hi:[1,0]
	v_cvt_pk_bf16_f32 v84, v86, v87
	v_pk_add_f32 v[88:89], v[88:89], 0 op_sel_hi:[1,0]
	v_cvt_pk_bf16_f32 v86, v82, v83
	v_and_b32_e32 v83, 0xffff0000, v84
	v_cvt_pk_bf16_f32 v85, v88, v89
	v_lshlrev_b32_e32 v82, 16, v84
	v_mul_f32_e32 v83, v83, v83
	v_and_b32_e32 v89, 0xffff0000, v85
	v_fmac_f32_e32 v83, v82, v82
	v_lshlrev_b32_e32 v88, 16, v85
	v_add_f32_e32 v82, v83, v100
	v_mul_f32_e32 v83, v89, v89
	v_cvt_pk_bf16_f32 v87, v98, v99
	v_and_b32_e32 v99, 0xffff0000, v86
	v_fmac_f32_e32 v83, v88, v88
	v_lshlrev_b32_e32 v98, 16, v86
	v_add_f32_e32 v82, v83, v82
	v_mul_f32_e32 v83, v99, v99
	v_and_b32_e32 v102, 0xffff0000, v87
	v_fmac_f32_e32 v83, v98, v98
	v_lshlrev_b32_e32 v101, 16, v87
	v_add_f32_e32 v82, v83, v82
	v_mul_f32_e32 v83, v102, v102
	v_fmac_f32_e32 v83, v101, v101
	v_add_f32_e32 v82, v83, v82
	ds_bpermute_b32 v83, v245, v82
	v_lshl_add_u64 v[88:89], s[88:89], 0, v[212:213]
	v_lshl_add_u64 v[88:89], v[204:205], 1, v[88:89]
	global_store_dwordx4 v[88:89], v[90:93], off
	global_store_dwordx4 v[88:89], v[84:87], off offset:256
	s_waitcnt lgkmcnt(0)
	v_add_f32_e32 v82, v82, v83
	ds_bpermute_b32 v83, v244, v82
	s_and_saveexec_b64 s[48:49], vcc
	s_cbranch_execz .LBB0_280
	v_lshlrev_b64 v[84:85], 6, v[210:211]
	v_lshl_add_u64 v[84:85], s[38:39], 0, v[84:85]
	v_lshl_add_u64 v[84:85], s[82:83], 2, v[84:85]
	s_lshl_b32 s76, s55, 2
	v_lshl_add_u64 v[84:85], v[84:85], 0, s[76:77]
	s_waitcnt lgkmcnt(0)
	v_add_f32_e32 v82, v82, v83
	global_store_dword v[84:85], v82, off
.LBB0_280:
	s_or_b64 exec, exec, s[48:49]
	s_waitcnt vmcnt(18)
	v_lshlrev_b32_e32 v82, 16, v166
	s_waitcnt lgkmcnt(0)
	v_and_b32_e32 v83, 0xffff0000, v166
	v_pk_fma_f32 v[78:79], v[78:79], 0.5, v[82:83] op_sel_hi:[1,0,1]
	v_lshlrev_b32_e32 v82, 16, v167
	v_and_b32_e32 v83, 0xffff0000, v167
	v_pk_fma_f32 v[80:81], v[80:81], 0.5, v[82:83] op_sel_hi:[1,0,1]
	v_lshlrev_b32_e32 v82, 16, v168
	v_and_b32_e32 v83, 0xffff0000, v168
	v_pk_fma_f32 v[74:75], v[74:75], 0.5, v[82:83] op_sel_hi:[1,0,1]
	v_pk_add_f32 v[78:79], v[78:79], 0 op_sel_hi:[1,0]
	v_pk_add_f32 v[82:83], v[74:75], 0 op_sel_hi:[1,0]
	v_lshlrev_b32_e32 v74, 16, v169
	v_and_b32_e32 v75, 0xffff0000, v169
	v_pk_fma_f32 v[74:75], v[76:77], 0.5, v[74:75] op_sel_hi:[1,0,1]
	v_pk_add_f32 v[80:81], v[80:81], 0 op_sel_hi:[1,0]
	v_pk_add_f32 v[84:85], v[74:75], 0 op_sel_hi:[1,0]
	v_cvt_pk_bf16_f32 v74, v78, v79
	v_cvt_pk_bf16_f32 v75, v80, v81
	v_and_b32_e32 v79, 0xffff0000, v74
	v_lshlrev_b32_e32 v78, 16, v74
	v_and_b32_e32 v81, 0xffff0000, v75
	v_mul_f32_e32 v79, v79, v79
	v_cvt_pk_bf16_f32 v76, v82, v83
	v_lshlrev_b32_e32 v80, 16, v75
	v_fmac_f32_e32 v79, v78, v78
	v_mul_f32_e32 v78, v81, v81
	v_and_b32_e32 v83, 0xffff0000, v76
	v_fmac_f32_e32 v78, v80, v80
	v_cvt_pk_bf16_f32 v77, v84, v85
	v_lshlrev_b32_e32 v82, 16, v76
	v_add_f32_e32 v78, v79, v78
	v_mul_f32_e32 v79, v83, v83
	v_and_b32_e32 v85, 0xffff0000, v77
	v_fmac_f32_e32 v79, v82, v82
	v_lshlrev_b32_e32 v84, 16, v77
	v_add_f32_e32 v78, v79, v78
	v_mul_f32_e32 v79, v85, v85
	v_fmac_f32_e32 v79, v84, v84
	v_add_f32_e32 v80, v79, v78
	s_waitcnt vmcnt(17)
	v_lshlrev_b32_e32 v78, 16, v162
	v_and_b32_e32 v79, 0xffff0000, v162
	v_pk_fma_f32 v[70:71], v[70:71], 0.5, v[78:79] op_sel_hi:[1,0,1]
	v_lshlrev_b32_e32 v78, 16, v163
	v_and_b32_e32 v79, 0xffff0000, v163
	v_pk_fma_f32 v[72:73], v[72:73], 0.5, v[78:79] op_sel_hi:[1,0,1]
	v_lshlrev_b32_e32 v78, 16, v164
	v_and_b32_e32 v79, 0xffff0000, v164
	v_pk_fma_f32 v[66:67], v[66:67], 0.5, v[78:79] op_sel_hi:[1,0,1]
	v_lshlrev_b32_e32 v78, 16, v165
	v_and_b32_e32 v79, 0xffff0000, v165
	v_pk_add_f32 v[70:71], v[70:71], 0 op_sel_hi:[1,0]
	v_pk_fma_f32 v[68:69], v[68:69], 0.5, v[78:79] op_sel_hi:[1,0,1]
	v_pk_add_f32 v[66:67], v[66:67], 0 op_sel_hi:[1,0]
	v_pk_add_f32 v[78:79], v[68:69], 0 op_sel_hi:[1,0]
	v_cvt_pk_bf16_f32 v68, v70, v71
	v_pk_add_f32 v[72:73], v[72:73], 0 op_sel_hi:[1,0]
	v_cvt_pk_bf16_f32 v70, v66, v67
	v_and_b32_e32 v67, 0xffff0000, v68
	v_cvt_pk_bf16_f32 v69, v72, v73
	v_lshlrev_b32_e32 v66, 16, v68
	v_mul_f32_e32 v67, v67, v67
	v_and_b32_e32 v73, 0xffff0000, v69
	v_fmac_f32_e32 v67, v66, v66
	v_lshlrev_b32_e32 v72, 16, v69
	v_add_f32_e32 v66, v67, v80
	v_mul_f32_e32 v67, v73, v73
	v_cvt_pk_bf16_f32 v71, v78, v79
	v_and_b32_e32 v79, 0xffff0000, v70
	v_fmac_f32_e32 v67, v72, v72
	v_lshlrev_b32_e32 v78, 16, v70
	v_add_f32_e32 v66, v67, v66
	v_mul_f32_e32 v67, v79, v79
	v_and_b32_e32 v82, 0xffff0000, v71
	v_fmac_f32_e32 v67, v78, v78
	v_lshlrev_b32_e32 v81, 16, v71
	v_add_f32_e32 v66, v67, v66
	v_mul_f32_e32 v67, v82, v82
	v_fmac_f32_e32 v67, v81, v81
	v_add_f32_e32 v66, v67, v66
	ds_bpermute_b32 v67, v245, v66
	v_lshl_add_u64 v[72:73], s[88:89], 0, v[228:229]
	v_lshl_add_u64 v[72:73], v[204:205], 1, v[72:73]
	global_store_dwordx4 v[72:73], v[74:77], off
	global_store_dwordx4 v[72:73], v[68:71], off offset:256
	s_waitcnt lgkmcnt(0)
	v_add_f32_e32 v66, v66, v67
	ds_bpermute_b32 v67, v244, v66
	s_and_saveexec_b64 s[48:49], vcc
	s_cbranch_execz .LBB0_282
	v_lshlrev_b64 v[68:69], 6, v[226:227]
	v_lshl_add_u64 v[68:69], s[38:39], 0, v[68:69]
	v_lshl_add_u64 v[68:69], s[82:83], 2, v[68:69]
	s_lshl_b32 s76, s55, 2
	v_lshl_add_u64 v[68:69], v[68:69], 0, s[76:77]
	s_waitcnt lgkmcnt(0)
	v_add_f32_e32 v66, v66, v67
	global_store_dword v[68:69], v66, off
.LBB0_282:
	s_or_b64 exec, exec, s[48:49]
	s_waitcnt vmcnt(19)
	v_lshlrev_b32_e32 v66, 16, v158
	s_waitcnt lgkmcnt(0)
	v_and_b32_e32 v67, 0xffff0000, v158
	v_pk_fma_f32 v[62:63], v[62:63], 0.5, v[66:67] op_sel_hi:[1,0,1]
	v_lshlrev_b32_e32 v66, 16, v159
	v_and_b32_e32 v67, 0xffff0000, v159
	v_pk_fma_f32 v[64:65], v[64:65], 0.5, v[66:67] op_sel_hi:[1,0,1]
	v_lshlrev_b32_e32 v66, 16, v160
	v_and_b32_e32 v67, 0xffff0000, v160
	v_pk_fma_f32 v[58:59], v[58:59], 0.5, v[66:67] op_sel_hi:[1,0,1]
	v_pk_add_f32 v[62:63], v[62:63], 0 op_sel_hi:[1,0]
	v_pk_add_f32 v[66:67], v[58:59], 0 op_sel_hi:[1,0]
	v_lshlrev_b32_e32 v58, 16, v161
	v_and_b32_e32 v59, 0xffff0000, v161
	v_pk_fma_f32 v[58:59], v[60:61], 0.5, v[58:59] op_sel_hi:[1,0,1]
	v_pk_add_f32 v[64:65], v[64:65], 0 op_sel_hi:[1,0]
	v_pk_add_f32 v[68:69], v[58:59], 0 op_sel_hi:[1,0]
	v_cvt_pk_bf16_f32 v58, v62, v63
	v_cvt_pk_bf16_f32 v59, v64, v65
	v_and_b32_e32 v63, 0xffff0000, v58
	v_lshlrev_b32_e32 v62, 16, v58
	v_and_b32_e32 v65, 0xffff0000, v59
	v_mul_f32_e32 v63, v63, v63
	v_cvt_pk_bf16_f32 v60, v66, v67
	v_lshlrev_b32_e32 v64, 16, v59
	v_fmac_f32_e32 v63, v62, v62
	v_mul_f32_e32 v62, v65, v65
	v_and_b32_e32 v67, 0xffff0000, v60
	v_fmac_f32_e32 v62, v64, v64
	v_cvt_pk_bf16_f32 v61, v68, v69
	v_lshlrev_b32_e32 v66, 16, v60
	v_add_f32_e32 v62, v63, v62
	v_mul_f32_e32 v63, v67, v67
	v_and_b32_e32 v69, 0xffff0000, v61
	v_fmac_f32_e32 v63, v66, v66
	v_lshlrev_b32_e32 v68, 16, v61
	v_add_f32_e32 v62, v63, v62
	v_mul_f32_e32 v63, v69, v69
	v_fmac_f32_e32 v63, v68, v68
	v_add_f32_e32 v64, v63, v62
	s_waitcnt vmcnt(18)
	v_lshlrev_b32_e32 v62, 16, v150
	v_and_b32_e32 v63, 0xffff0000, v150
	v_pk_fma_f32 v[54:55], v[54:55], 0.5, v[62:63] op_sel_hi:[1,0,1]
	v_lshlrev_b32_e32 v62, 16, v151
	v_and_b32_e32 v63, 0xffff0000, v151
	v_pk_fma_f32 v[56:57], v[56:57], 0.5, v[62:63] op_sel_hi:[1,0,1]
	v_lshlrev_b32_e32 v62, 16, v152
	v_and_b32_e32 v63, 0xffff0000, v152
	v_pk_fma_f32 v[50:51], v[50:51], 0.5, v[62:63] op_sel_hi:[1,0,1]
	v_lshlrev_b32_e32 v62, 16, v153
	v_and_b32_e32 v63, 0xffff0000, v153
	v_pk_add_f32 v[54:55], v[54:55], 0 op_sel_hi:[1,0]
	v_pk_fma_f32 v[52:53], v[52:53], 0.5, v[62:63] op_sel_hi:[1,0,1]
	v_pk_add_f32 v[50:51], v[50:51], 0 op_sel_hi:[1,0]
	v_pk_add_f32 v[62:63], v[52:53], 0 op_sel_hi:[1,0]
	v_cvt_pk_bf16_f32 v52, v54, v55
	v_pk_add_f32 v[56:57], v[56:57], 0 op_sel_hi:[1,0]
	v_cvt_pk_bf16_f32 v54, v50, v51
	v_and_b32_e32 v51, 0xffff0000, v52
	v_cvt_pk_bf16_f32 v53, v56, v57
	v_lshlrev_b32_e32 v50, 16, v52
	v_mul_f32_e32 v51, v51, v51
	v_and_b32_e32 v57, 0xffff0000, v53
	v_fmac_f32_e32 v51, v50, v50
	v_lshlrev_b32_e32 v56, 16, v53
	v_add_f32_e32 v50, v51, v64
	v_mul_f32_e32 v51, v57, v57
	v_cvt_pk_bf16_f32 v55, v62, v63
	v_and_b32_e32 v63, 0xffff0000, v54
	v_fmac_f32_e32 v51, v56, v56
	v_lshlrev_b32_e32 v62, 16, v54
	v_add_f32_e32 v50, v51, v50
	v_mul_f32_e32 v51, v63, v63
	v_and_b32_e32 v66, 0xffff0000, v55
	v_fmac_f32_e32 v51, v62, v62
	v_lshlrev_b32_e32 v65, 16, v55
	v_add_f32_e32 v50, v51, v50
	v_mul_f32_e32 v51, v66, v66
	v_fmac_f32_e32 v51, v65, v65
	v_add_f32_e32 v50, v51, v50
	ds_bpermute_b32 v51, v245, v50
	v_lshl_add_u64 v[56:57], s[88:89], 0, v[224:225]
	v_lshl_add_u64 v[56:57], v[204:205], 1, v[56:57]
	global_store_dwordx4 v[56:57], v[58:61], off
	global_store_dwordx4 v[56:57], v[52:55], off offset:256
	s_waitcnt lgkmcnt(0)
	v_add_f32_e32 v50, v50, v51
	ds_bpermute_b32 v51, v244, v50
	s_and_saveexec_b64 s[48:49], vcc
	s_cbranch_execz .LBB0_284
	v_lshlrev_b64 v[52:53], 6, v[222:223]
	v_lshl_add_u64 v[52:53], s[38:39], 0, v[52:53]
	v_lshl_add_u64 v[52:53], s[82:83], 2, v[52:53]
	s_lshl_b32 s76, s55, 2
	v_lshl_add_u64 v[52:53], v[52:53], 0, s[76:77]
	s_waitcnt lgkmcnt(0)
	v_add_f32_e32 v50, v50, v51
	global_store_dword v[52:53], v50, off
.LBB0_284:
	s_or_b64 exec, exec, s[48:49]
	s_waitcnt vmcnt(20)
	v_lshlrev_b32_e32 v50, 16, v142
	s_waitcnt lgkmcnt(0)
	v_and_b32_e32 v51, 0xffff0000, v142
	v_pk_fma_f32 v[46:47], v[46:47], 0.5, v[50:51] op_sel_hi:[1,0,1]
	v_lshlrev_b32_e32 v50, 16, v143
	v_and_b32_e32 v51, 0xffff0000, v143
	v_pk_fma_f32 v[48:49], v[48:49], 0.5, v[50:51] op_sel_hi:[1,0,1]
	v_lshlrev_b32_e32 v50, 16, v144
	v_and_b32_e32 v51, 0xffff0000, v144
	v_pk_fma_f32 v[42:43], v[42:43], 0.5, v[50:51] op_sel_hi:[1,0,1]
	v_pk_add_f32 v[46:47], v[46:47], 0 op_sel_hi:[1,0]
	v_pk_add_f32 v[50:51], v[42:43], 0 op_sel_hi:[1,0]
	v_lshlrev_b32_e32 v42, 16, v145
	v_and_b32_e32 v43, 0xffff0000, v145
	v_pk_fma_f32 v[42:43], v[44:45], 0.5, v[42:43] op_sel_hi:[1,0,1]
	v_pk_add_f32 v[48:49], v[48:49], 0 op_sel_hi:[1,0]
	v_pk_add_f32 v[52:53], v[42:43], 0 op_sel_hi:[1,0]
	v_cvt_pk_bf16_f32 v42, v46, v47
	v_cvt_pk_bf16_f32 v43, v48, v49
	v_and_b32_e32 v47, 0xffff0000, v42
	v_lshlrev_b32_e32 v46, 16, v42
	v_and_b32_e32 v49, 0xffff0000, v43
	v_mul_f32_e32 v47, v47, v47
	v_cvt_pk_bf16_f32 v44, v50, v51
	v_lshlrev_b32_e32 v48, 16, v43
	v_fmac_f32_e32 v47, v46, v46
	v_mul_f32_e32 v46, v49, v49
	v_and_b32_e32 v51, 0xffff0000, v44
	v_fmac_f32_e32 v46, v48, v48
	v_cvt_pk_bf16_f32 v45, v52, v53
	v_lshlrev_b32_e32 v50, 16, v44
	v_add_f32_e32 v46, v47, v46
	v_mul_f32_e32 v47, v51, v51
	v_and_b32_e32 v53, 0xffff0000, v45
	v_fmac_f32_e32 v47, v50, v50
	v_lshlrev_b32_e32 v52, 16, v45
	v_add_f32_e32 v46, v47, v46
	v_mul_f32_e32 v47, v53, v53
	v_fmac_f32_e32 v47, v52, v52
	v_add_f32_e32 v48, v47, v46
	s_waitcnt vmcnt(19)
	v_lshlrev_b32_e32 v46, 16, v138
	v_and_b32_e32 v47, 0xffff0000, v138
	v_pk_fma_f32 v[38:39], v[38:39], 0.5, v[46:47] op_sel_hi:[1,0,1]
	v_lshlrev_b32_e32 v46, 16, v139
	v_and_b32_e32 v47, 0xffff0000, v139
	v_pk_fma_f32 v[40:41], v[40:41], 0.5, v[46:47] op_sel_hi:[1,0,1]
	v_lshlrev_b32_e32 v46, 16, v140
	v_and_b32_e32 v47, 0xffff0000, v140
	v_pk_fma_f32 v[34:35], v[34:35], 0.5, v[46:47] op_sel_hi:[1,0,1]
	v_lshlrev_b32_e32 v46, 16, v141
	v_and_b32_e32 v47, 0xffff0000, v141
	v_pk_add_f32 v[38:39], v[38:39], 0 op_sel_hi:[1,0]
	v_pk_fma_f32 v[36:37], v[36:37], 0.5, v[46:47] op_sel_hi:[1,0,1]
	v_pk_add_f32 v[34:35], v[34:35], 0 op_sel_hi:[1,0]
	v_pk_add_f32 v[46:47], v[36:37], 0 op_sel_hi:[1,0]
	v_cvt_pk_bf16_f32 v36, v38, v39
	v_pk_add_f32 v[40:41], v[40:41], 0 op_sel_hi:[1,0]
	v_cvt_pk_bf16_f32 v38, v34, v35
	v_and_b32_e32 v35, 0xffff0000, v36
	v_cvt_pk_bf16_f32 v37, v40, v41
	v_lshlrev_b32_e32 v34, 16, v36
	v_mul_f32_e32 v35, v35, v35
	v_and_b32_e32 v41, 0xffff0000, v37
	v_fmac_f32_e32 v35, v34, v34
	v_lshlrev_b32_e32 v40, 16, v37
	v_add_f32_e32 v34, v35, v48
	v_mul_f32_e32 v35, v41, v41
	v_cvt_pk_bf16_f32 v39, v46, v47
	v_and_b32_e32 v47, 0xffff0000, v38
	v_fmac_f32_e32 v35, v40, v40
	v_lshlrev_b32_e32 v46, 16, v38
	v_add_f32_e32 v34, v35, v34
	v_mul_f32_e32 v35, v47, v47
	v_and_b32_e32 v50, 0xffff0000, v39
	v_fmac_f32_e32 v35, v46, v46
	v_lshlrev_b32_e32 v49, 16, v39
	v_add_f32_e32 v34, v35, v34
	v_mul_f32_e32 v35, v50, v50
	v_fmac_f32_e32 v35, v49, v49
	v_add_f32_e32 v34, v35, v34
	ds_bpermute_b32 v35, v245, v34
	v_lshl_add_u64 v[40:41], s[88:89], 0, v[220:221]
	v_lshl_add_u64 v[40:41], v[204:205], 1, v[40:41]
	global_store_dwordx4 v[40:41], v[42:45], off
	global_store_dwordx4 v[40:41], v[36:39], off offset:256
	s_waitcnt lgkmcnt(0)
	v_add_f32_e32 v34, v34, v35
	ds_bpermute_b32 v35, v244, v34
	s_and_saveexec_b64 s[48:49], vcc
	s_cbranch_execz .LBB0_286
	v_lshlrev_b64 v[36:37], 6, v[218:219]
	v_lshl_add_u64 v[36:37], s[38:39], 0, v[36:37]
	v_lshl_add_u64 v[36:37], s[82:83], 2, v[36:37]
	s_lshl_b32 s76, s55, 2
	v_lshl_add_u64 v[36:37], v[36:37], 0, s[76:77]
	s_waitcnt lgkmcnt(0)
	v_add_f32_e32 v34, v34, v35
	global_store_dword v[36:37], v34, off
.LBB0_286:
	s_or_b64 exec, exec, s[48:49]
	s_waitcnt vmcnt(21)
	v_lshlrev_b32_e32 v34, 16, v126
	s_waitcnt lgkmcnt(0)
	v_and_b32_e32 v35, 0xffff0000, v126
	v_pk_fma_f32 v[30:31], v[30:31], 0.5, v[34:35] op_sel_hi:[1,0,1]
	v_lshlrev_b32_e32 v34, 16, v127
	v_and_b32_e32 v35, 0xffff0000, v127
	v_pk_fma_f32 v[32:33], v[32:33], 0.5, v[34:35] op_sel_hi:[1,0,1]
	v_lshlrev_b32_e32 v34, 16, v128
	v_and_b32_e32 v35, 0xffff0000, v128
	v_pk_fma_f32 v[26:27], v[26:27], 0.5, v[34:35] op_sel_hi:[1,0,1]
	v_pk_add_f32 v[30:31], v[30:31], 0 op_sel_hi:[1,0]
	v_pk_add_f32 v[34:35], v[26:27], 0 op_sel_hi:[1,0]
	v_lshlrev_b32_e32 v26, 16, v129
	v_and_b32_e32 v27, 0xffff0000, v129
	v_pk_fma_f32 v[26:27], v[28:29], 0.5, v[26:27] op_sel_hi:[1,0,1]
	v_pk_add_f32 v[32:33], v[32:33], 0 op_sel_hi:[1,0]
	v_pk_add_f32 v[36:37], v[26:27], 0 op_sel_hi:[1,0]
	v_cvt_pk_bf16_f32 v26, v30, v31
	v_cvt_pk_bf16_f32 v27, v32, v33
	v_and_b32_e32 v31, 0xffff0000, v26
	v_lshlrev_b32_e32 v30, 16, v26
	v_and_b32_e32 v33, 0xffff0000, v27
	v_mul_f32_e32 v31, v31, v31
	v_cvt_pk_bf16_f32 v28, v34, v35
	v_lshlrev_b32_e32 v32, 16, v27
	v_fmac_f32_e32 v31, v30, v30
	v_mul_f32_e32 v30, v33, v33
	v_and_b32_e32 v35, 0xffff0000, v28
	v_fmac_f32_e32 v30, v32, v32
	v_cvt_pk_bf16_f32 v29, v36, v37
	v_lshlrev_b32_e32 v34, 16, v28
	v_add_f32_e32 v30, v31, v30
	v_mul_f32_e32 v31, v35, v35
	v_and_b32_e32 v37, 0xffff0000, v29
	v_fmac_f32_e32 v31, v34, v34
	v_lshlrev_b32_e32 v36, 16, v29
	v_add_f32_e32 v30, v31, v30
	v_mul_f32_e32 v31, v37, v37
	v_fmac_f32_e32 v31, v36, v36
	v_add_f32_e32 v32, v31, v30
	s_waitcnt vmcnt(20)
	v_lshlrev_b32_e32 v30, 16, v114
	v_and_b32_e32 v31, 0xffff0000, v114
	v_pk_fma_f32 v[22:23], v[22:23], 0.5, v[30:31] op_sel_hi:[1,0,1]
	v_lshlrev_b32_e32 v30, 16, v115
	v_and_b32_e32 v31, 0xffff0000, v115
	v_pk_fma_f32 v[24:25], v[24:25], 0.5, v[30:31] op_sel_hi:[1,0,1]
	v_lshlrev_b32_e32 v30, 16, v116
	v_and_b32_e32 v31, 0xffff0000, v116
	v_pk_fma_f32 v[18:19], v[18:19], 0.5, v[30:31] op_sel_hi:[1,0,1]
	v_lshlrev_b32_e32 v30, 16, v117
	v_and_b32_e32 v31, 0xffff0000, v117
	v_pk_add_f32 v[22:23], v[22:23], 0 op_sel_hi:[1,0]
	v_pk_fma_f32 v[20:21], v[20:21], 0.5, v[30:31] op_sel_hi:[1,0,1]
	v_pk_add_f32 v[18:19], v[18:19], 0 op_sel_hi:[1,0]
	v_pk_add_f32 v[30:31], v[20:21], 0 op_sel_hi:[1,0]
	v_cvt_pk_bf16_f32 v20, v22, v23
	v_pk_add_f32 v[24:25], v[24:25], 0 op_sel_hi:[1,0]
	v_cvt_pk_bf16_f32 v22, v18, v19
	v_and_b32_e32 v19, 0xffff0000, v20
	v_cvt_pk_bf16_f32 v21, v24, v25
	v_lshlrev_b32_e32 v18, 16, v20
	v_mul_f32_e32 v19, v19, v19
	v_and_b32_e32 v25, 0xffff0000, v21
	v_fmac_f32_e32 v19, v18, v18
	v_lshlrev_b32_e32 v24, 16, v21
	v_add_f32_e32 v18, v19, v32
	v_mul_f32_e32 v19, v25, v25
	v_cvt_pk_bf16_f32 v23, v30, v31
	v_and_b32_e32 v31, 0xffff0000, v22
	v_fmac_f32_e32 v19, v24, v24
	v_lshlrev_b32_e32 v30, 16, v22
	v_add_f32_e32 v18, v19, v18
	v_mul_f32_e32 v19, v31, v31
	v_and_b32_e32 v34, 0xffff0000, v23
	v_fmac_f32_e32 v19, v30, v30
	v_lshlrev_b32_e32 v33, 16, v23
	v_add_f32_e32 v18, v19, v18
	v_mul_f32_e32 v19, v34, v34
	v_fmac_f32_e32 v19, v33, v33
	v_add_f32_e32 v18, v19, v18
	ds_bpermute_b32 v19, v245, v18
	v_lshl_add_u64 v[24:25], s[88:89], 0, v[216:217]
	v_lshl_add_u64 v[24:25], v[204:205], 1, v[24:25]
	global_store_dwordx4 v[24:25], v[26:29], off
	global_store_dwordx4 v[24:25], v[20:23], off offset:256
	s_waitcnt lgkmcnt(0)
	v_add_f32_e32 v18, v18, v19
	ds_bpermute_b32 v19, v244, v18
	s_and_saveexec_b64 s[48:49], vcc
	s_cbranch_execz .LBB0_288
	v_lshlrev_b64 v[20:21], 6, v[214:215]
	v_lshl_add_u64 v[20:21], s[38:39], 0, v[20:21]
	v_lshl_add_u64 v[20:21], s[82:83], 2, v[20:21]
	s_lshl_b32 s76, s55, 2
	v_lshl_add_u64 v[20:21], v[20:21], 0, s[76:77]
	s_waitcnt lgkmcnt(0)
	v_add_f32_e32 v18, v18, v19
	global_store_dword v[20:21], v18, off
.LBB0_288:
	s_or_b64 exec, exec, s[48:49]
	s_waitcnt vmcnt(22)
	v_lshlrev_b32_e32 v18, 16, v106
	s_waitcnt lgkmcnt(0)
	v_and_b32_e32 v19, 0xffff0000, v106
	v_pk_fma_f32 v[14:15], v[14:15], 0.5, v[18:19] op_sel_hi:[1,0,1]
	v_lshlrev_b32_e32 v18, 16, v107
	v_and_b32_e32 v19, 0xffff0000, v107
	v_pk_fma_f32 v[16:17], v[16:17], 0.5, v[18:19] op_sel_hi:[1,0,1]
	v_lshlrev_b32_e32 v18, 16, v108
	v_and_b32_e32 v19, 0xffff0000, v108
	v_pk_fma_f32 v[10:11], v[10:11], 0.5, v[18:19] op_sel_hi:[1,0,1]
	v_pk_add_f32 v[14:15], v[14:15], 0 op_sel_hi:[1,0]
	v_pk_add_f32 v[18:19], v[10:11], 0 op_sel_hi:[1,0]
	v_lshlrev_b32_e32 v10, 16, v109
	v_and_b32_e32 v11, 0xffff0000, v109
	v_pk_fma_f32 v[10:11], v[12:13], 0.5, v[10:11] op_sel_hi:[1,0,1]
	v_pk_add_f32 v[16:17], v[16:17], 0 op_sel_hi:[1,0]
	v_pk_add_f32 v[20:21], v[10:11], 0 op_sel_hi:[1,0]
	v_cvt_pk_bf16_f32 v10, v14, v15
	v_cvt_pk_bf16_f32 v11, v16, v17
	v_and_b32_e32 v15, 0xffff0000, v10
	v_lshlrev_b32_e32 v14, 16, v10
	v_and_b32_e32 v17, 0xffff0000, v11
	v_mul_f32_e32 v15, v15, v15
	v_cvt_pk_bf16_f32 v12, v18, v19
	v_lshlrev_b32_e32 v16, 16, v11
	v_fmac_f32_e32 v15, v14, v14
	v_mul_f32_e32 v14, v17, v17
	v_and_b32_e32 v19, 0xffff0000, v12
	v_fmac_f32_e32 v14, v16, v16
	v_cvt_pk_bf16_f32 v13, v20, v21
	v_lshlrev_b32_e32 v18, 16, v12
	v_add_f32_e32 v14, v15, v14
	v_mul_f32_e32 v15, v19, v19
	v_and_b32_e32 v21, 0xffff0000, v13
	v_fmac_f32_e32 v15, v18, v18
	v_lshlrev_b32_e32 v20, 16, v13
	v_add_f32_e32 v14, v15, v14
	v_mul_f32_e32 v15, v21, v21
	v_fmac_f32_e32 v15, v20, v20
	v_add_f32_e32 v16, v15, v14
	s_waitcnt vmcnt(21)
	v_lshlrev_b32_e32 v14, 16, v94
	v_and_b32_e32 v15, 0xffff0000, v94
	v_pk_fma_f32 v[6:7], v[6:7], 0.5, v[14:15] op_sel_hi:[1,0,1]
	v_lshlrev_b32_e32 v14, 16, v95
	v_and_b32_e32 v15, 0xffff0000, v95
	v_pk_fma_f32 v[8:9], v[8:9], 0.5, v[14:15] op_sel_hi:[1,0,1]
	v_lshlrev_b32_e32 v14, 16, v96
	v_and_b32_e32 v15, 0xffff0000, v96
	v_pk_fma_f32 v[2:3], v[2:3], 0.5, v[14:15] op_sel_hi:[1,0,1]
	v_lshlrev_b32_e32 v14, 16, v97
	v_and_b32_e32 v15, 0xffff0000, v97
	v_pk_add_f32 v[6:7], v[6:7], 0 op_sel_hi:[1,0]
	v_pk_fma_f32 v[4:5], v[4:5], 0.5, v[14:15] op_sel_hi:[1,0,1]
	v_pk_add_f32 v[2:3], v[2:3], 0 op_sel_hi:[1,0]
	v_pk_add_f32 v[14:15], v[4:5], 0 op_sel_hi:[1,0]
	v_cvt_pk_bf16_f32 v4, v6, v7
	v_pk_add_f32 v[8:9], v[8:9], 0 op_sel_hi:[1,0]
	v_cvt_pk_bf16_f32 v6, v2, v3
	v_and_b32_e32 v3, 0xffff0000, v4
	v_cvt_pk_bf16_f32 v5, v8, v9
	v_lshlrev_b32_e32 v2, 16, v4
	v_mul_f32_e32 v3, v3, v3
	v_and_b32_e32 v9, 0xffff0000, v5
	v_fmac_f32_e32 v3, v2, v2
	v_lshlrev_b32_e32 v8, 16, v5
	v_add_f32_e32 v2, v3, v16
	v_mul_f32_e32 v3, v9, v9
	v_cvt_pk_bf16_f32 v7, v14, v15
	v_and_b32_e32 v15, 0xffff0000, v6
	v_fmac_f32_e32 v3, v8, v8
	v_lshlrev_b32_e32 v14, 16, v6
	v_add_f32_e32 v2, v3, v2
	v_mul_f32_e32 v3, v15, v15
	v_and_b32_e32 v18, 0xffff0000, v7
	v_fmac_f32_e32 v3, v14, v14
	v_lshlrev_b32_e32 v17, 16, v7
	v_add_f32_e32 v2, v3, v2
	v_mul_f32_e32 v3, v18, v18
	v_fmac_f32_e32 v3, v17, v17
	v_add_f32_e32 v2, v3, v2
	ds_bpermute_b32 v3, v245, v2
	v_lshl_add_u64 v[8:9], s[88:89], 0, v[208:209]
	v_lshl_add_u64 v[8:9], v[204:205], 1, v[8:9]
	global_store_dwordx4 v[8:9], v[10:13], off
	global_store_dwordx4 v[8:9], v[4:7], off offset:256
	s_waitcnt lgkmcnt(0)
	v_add_f32_e32 v2, v2, v3
	ds_bpermute_b32 v3, v244, v2
	s_and_saveexec_b64 s[48:49], vcc
	s_cbranch_execz .LBB0_290
	v_lshlrev_b64 v[4:5], 6, v[206:207]
	v_lshl_add_u64 v[4:5], s[38:39], 0, v[4:5]
	v_lshl_add_u64 v[4:5], s[82:83], 2, v[4:5]
	s_lshl_b32 s76, s55, 2
	v_lshl_add_u64 v[4:5], v[4:5], 0, s[76:77]
	s_waitcnt lgkmcnt(0)
	v_add_f32_e32 v2, v2, v3
	global_store_dword v[4:5], v2, off

.LBB0_831:
	s_lshl_b32 s9, s21, 8
	s_add_i32 s9, s9, s55
	v_and_or_b32 v228, v124, 15, s9
	v_lshlrev_b64 v[232:233], 1, v[224:225]
	v_ashrrev_i32_e32 v229, 31, v228
	v_lshl_add_u64 v[122:123], s[88:89], 0, v[232:233]
	v_lshlrev_b64 v[236:237], 11, v[228:229]
	v_lshlrev_b32_e32 v212, 2, v124
	v_cmp_gt_u32_e32 vcc, 16, v124
	v_lshl_add_u64 v[124:125], v[122:123], 0, v[236:237]
	global_load_dwordx4 v[206:209], v[124:125], off
	global_load_dwordx4 v[202:205], v[124:125], off offset:256
	v_or_b32_e32 v210, 16, v228
	v_ashrrev_i32_e32 v211, 31, v210
	v_lshlrev_b64 v[124:125], 11, v[210:211]
	v_or_b32_e32 v246, 32, v228
	v_lshl_add_u64 v[124:125], v[122:123], 0, v[124:125]
	v_ashrrev_i32_e32 v247, 31, v246
	global_load_dwordx4 v[198:201], v[124:125], off
	global_load_dwordx4 v[194:197], v[124:125], off offset:256
	v_lshlrev_b64 v[124:125], 11, v[246:247]
	v_or_b32_e32 v242, 48, v228
	v_lshl_add_u64 v[124:125], v[122:123], 0, v[124:125]
	v_ashrrev_i32_e32 v243, 31, v242
	global_load_dwordx4 v[190:193], v[124:125], off
	global_load_dwordx4 v[186:189], v[124:125], off offset:256
	v_lshlrev_b64 v[124:125], 11, v[242:243]
	v_add_u32_e32 v238, 0x80, v228
	v_lshl_add_u64 v[124:125], v[122:123], 0, v[124:125]
	v_ashrrev_i32_e32 v239, 31, v238
	global_load_dwordx4 v[182:185], v[124:125], off
	global_load_dwordx4 v[178:181], v[124:125], off offset:256
	v_lshlrev_b64 v[124:125], 11, v[238:239]
	v_add_u32_e32 v234, 0x90, v228
	v_lshl_add_u64 v[124:125], v[122:123], 0, v[124:125]
	v_ashrrev_i32_e32 v235, 31, v234
	global_load_dwordx4 v[166:169], v[124:125], off
	global_load_dwordx4 v[162:165], v[124:125], off offset:256
	v_lshlrev_b64 v[124:125], 11, v[234:235]
	v_add_u32_e32 v230, 0xa0, v228
	v_lshl_add_u64 v[124:125], v[122:123], 0, v[124:125]
	v_ashrrev_i32_e32 v231, 31, v230
	global_load_dwordx4 v[158:161], v[124:125], off
	global_load_dwordx4 v[154:157], v[124:125], off offset:256
	v_lshlrev_b64 v[124:125], 11, v[230:231]
	v_add_u32_e32 v226, 0xb0, v228
	v_lshl_add_u64 v[124:125], v[122:123], 0, v[124:125]
	v_ashrrev_i32_e32 v227, 31, v226
	global_load_dwordx4 v[150:153], v[124:125], off
	global_load_dwordx4 v[138:141], v[124:125], off offset:256
	v_lshlrev_b64 v[124:125], 11, v[226:227]
	v_lshl_add_u64 v[122:123], v[122:123], 0, v[124:125]
	global_load_dwordx4 v[130:133], v[122:123], off
	s_nop 0
	global_load_dwordx4 v[122:125], v[122:123], off offset:256
	v_xor_b32_e32 v249, 64, v212
	v_xor_b32_e32 v248, 0x80, v212
	s_lshl_b32 s10, s20, 2
	s_ashr_i32 s11, s10, 31
	s_waitcnt vmcnt(15)
	v_lshlrev_b32_e32 v212, 16, v206
	v_and_b32_e32 v213, 0xffff0000, v206
	v_lshlrev_b32_e32 v206, 16, v207
	v_and_b32_e32 v207, 0xffff0000, v207
	v_pk_add_f32 v[176:177], v[176:177], v[206:207]
	v_lshlrev_b32_e32 v206, 16, v208
	v_and_b32_e32 v207, 0xffff0000, v208
	v_pk_add_f32 v[174:175], v[174:175], v[212:213]
	v_pk_add_f32 v[170:171], v[170:171], v[206:207]
	v_lshlrev_b32_e32 v206, 16, v209
	v_and_b32_e32 v207, 0xffff0000, v209
	v_pk_add_f32 v[174:175], v[106:107], v[174:175]
	v_pk_add_f32 v[170:171], v[94:95], v[170:171]
	v_pk_add_f32 v[172:173], v[172:173], v[206:207]
	v_pk_add_f32 v[176:177], v[108:109], v[176:177]
	v_pk_add_f32 v[206:207], v[96:97], v[172:173]
	v_cvt_pk_bf16_f32 v172, v174, v175
	v_cvt_pk_bf16_f32 v174, v170, v171
	v_lshl_add_u64 v[170:171], s[88:89], 0, v[236:237]
	v_cvt_pk_bf16_f32 v173, v176, v177
	v_cvt_pk_bf16_f32 v175, v206, v207
	v_lshl_add_u64 v[170:171], v[170:171], 0, v[232:233]
	global_store_dwordx4 v[170:171], v[172:175], off
	v_lshlrev_b32_e32 v176, 16, v172
	v_lshlrev_b32_e32 v177, 16, v173
	v_and_b32_e32 v172, 0xffff0000, v172
	v_and_b32_e32 v173, 0xffff0000, v173
	v_mul_f32_e32 v172, v172, v172
	v_mul_f32_e32 v173, v173, v173
	v_lshlrev_b32_e32 v206, 16, v174
	v_and_b32_e32 v174, 0xffff0000, v174
	v_fmac_f32_e32 v172, v176, v176
	v_fmac_f32_e32 v173, v177, v177
	v_add_f32_e32 v172, v172, v173
	v_mul_f32_e32 v173, v174, v174
	v_lshlrev_b32_e32 v207, 16, v175
	v_and_b32_e32 v175, 0xffff0000, v175
	v_fmac_f32_e32 v173, v206, v206
	v_add_f32_e32 v172, v173, v172
	v_mul_f32_e32 v173, v175, v175
	v_fmac_f32_e32 v173, v207, v207
	v_add_f32_e32 v176, v173, v172
	s_waitcnt vmcnt(15)
	v_lshlrev_b32_e32 v172, 16, v202
	v_and_b32_e32 v173, 0xffff0000, v202
	v_pk_add_f32 v[146:147], v[146:147], v[172:173]
	v_lshlrev_b32_e32 v172, 16, v203
	v_and_b32_e32 v173, 0xffff0000, v203
	v_pk_add_f32 v[148:149], v[148:149], v[172:173]
	v_lshlrev_b32_e32 v172, 16, v204
	v_and_b32_e32 v173, 0xffff0000, v204
	v_pk_add_f32 v[142:143], v[142:143], v[172:173]
	v_pk_add_f32 v[146:147], v[102:103], v[146:147]
	v_pk_add_f32 v[172:173], v[90:91], v[142:143]
	v_lshlrev_b32_e32 v142, 16, v205
	v_and_b32_e32 v143, 0xffff0000, v205
	v_pk_add_f32 v[142:143], v[144:145], v[142:143]
	v_pk_add_f32 v[148:149], v[104:105], v[148:149]
	v_pk_add_f32 v[174:175], v[92:93], v[142:143]
	v_cvt_pk_bf16_f32 v142, v146, v147
	v_cvt_pk_bf16_f32 v143, v148, v149
	v_cvt_pk_bf16_f32 v144, v172, v173
	v_cvt_pk_bf16_f32 v145, v174, v175
	global_store_dwordx4 v[170:171], v[142:145], off offset:256
	v_lshlrev_b32_e32 v146, 16, v142
	v_lshlrev_b32_e32 v147, 16, v143
	v_and_b32_e32 v142, 0xffff0000, v142
	v_and_b32_e32 v143, 0xffff0000, v143
	v_mul_f32_e32 v142, v142, v142
	v_fmac_f32_e32 v142, v146, v146
	v_mul_f32_e32 v143, v143, v143
	v_lshlrev_b32_e32 v148, 16, v144
	v_and_b32_e32 v144, 0xffff0000, v144
	v_add_f32_e32 v142, v142, v176
	v_fmac_f32_e32 v143, v147, v147
	v_add_f32_e32 v142, v143, v142
	v_mul_f32_e32 v143, v144, v144
	v_lshlrev_b32_e32 v149, 16, v145
	v_and_b32_e32 v145, 0xffff0000, v145
	v_fmac_f32_e32 v143, v148, v148
	v_add_f32_e32 v142, v143, v142
	v_mul_f32_e32 v143, v145, v145
	v_fmac_f32_e32 v143, v149, v149
	v_add_f32_e32 v142, v143, v142
	ds_bpermute_b32 v143, v249, v142
	s_waitcnt lgkmcnt(0)
	v_add_f32_e32 v142, v142, v143
	ds_bpermute_b32 v143, v248, v142
	s_and_saveexec_b64 s[42:43], vcc
	s_cbranch_execz .LBB0_833
	v_lshlrev_b64 v[144:145], 6, v[228:229]
	v_lshl_add_u64 v[144:145], s[68:69], 0, v[144:145]
	v_lshl_add_u64 v[144:145], s[10:11], 2, v[144:145]
	s_lshl_b32 s76, s54, 2
	v_lshl_add_u64 v[144:145], v[144:145], 0, s[76:77]
	s_waitcnt lgkmcnt(0)
	v_add_f32_e32 v142, v142, v143
	global_store_dword v[144:145], v142, off
.LBB0_833:
	s_or_b64 exec, exec, s[42:43]
	s_waitcnt vmcnt(16)
	v_lshlrev_b32_e32 v142, 16, v198
	s_waitcnt lgkmcnt(0)
	v_and_b32_e32 v143, 0xffff0000, v198
	v_pk_add_f32 v[134:135], v[134:135], v[142:143]
	v_lshlrev_b32_e32 v142, 16, v199
	v_and_b32_e32 v143, 0xffff0000, v199
	v_pk_add_f32 v[136:137], v[136:137], v[142:143]
	v_lshlrev_b32_e32 v142, 16, v200
	v_and_b32_e32 v143, 0xffff0000, v200
	v_pk_add_f32 v[126:127], v[126:127], v[142:143]
	v_pk_add_f32 v[134:135], v[106:107], v[134:135]
	v_pk_add_f32 v[142:143], v[94:95], v[126:127]
	v_lshlrev_b32_e32 v126, 16, v201
	v_and_b32_e32 v127, 0xffff0000, v201
	v_pk_add_f32 v[126:127], v[128:129], v[126:127]
	v_pk_add_f32 v[136:137], v[108:109], v[136:137]
	v_pk_add_f32 v[144:145], v[96:97], v[126:127]
	v_cvt_pk_bf16_f32 v126, v134, v135
	v_cvt_pk_bf16_f32 v127, v136, v137
	v_and_b32_e32 v135, 0xffff0000, v126
	v_lshlrev_b32_e32 v134, 16, v126
	v_and_b32_e32 v137, 0xffff0000, v127
	v_mul_f32_e32 v135, v135, v135
	v_cvt_pk_bf16_f32 v128, v142, v143
	v_lshlrev_b32_e32 v136, 16, v127
	v_fmac_f32_e32 v135, v134, v134
	v_mul_f32_e32 v134, v137, v137
	v_and_b32_e32 v143, 0xffff0000, v128
	v_fmac_f32_e32 v134, v136, v136
	v_cvt_pk_bf16_f32 v129, v144, v145
	v_lshlrev_b32_e32 v142, 16, v128
	v_add_f32_e32 v134, v135, v134
	v_mul_f32_e32 v135, v143, v143
	v_and_b32_e32 v145, 0xffff0000, v129
	v_fmac_f32_e32 v135, v142, v142
	v_lshlrev_b32_e32 v144, 16, v129
	v_add_f32_e32 v134, v135, v134
	v_mul_f32_e32 v135, v145, v145
	v_fmac_f32_e32 v135, v144, v144
	v_add_f32_e32 v136, v135, v134
	s_waitcnt vmcnt(15)
	v_lshlrev_b32_e32 v134, 16, v194
	v_and_b32_e32 v135, 0xffff0000, v194
	v_pk_add_f32 v[118:119], v[118:119], v[134:135]
	v_lshlrev_b32_e32 v134, 16, v195
	v_and_b32_e32 v135, 0xffff0000, v195
	v_pk_add_f32 v[120:121], v[120:121], v[134:135]
	v_lshlrev_b32_e32 v134, 16, v196
	v_and_b32_e32 v135, 0xffff0000, v196
	v_pk_add_f32 v[114:115], v[114:115], v[134:135]
	v_lshlrev_b32_e32 v134, 16, v197
	v_and_b32_e32 v135, 0xffff0000, v197
	v_pk_add_f32 v[118:119], v[102:103], v[118:119]
	v_pk_add_f32 v[116:117], v[116:117], v[134:135]
	v_pk_add_f32 v[114:115], v[90:91], v[114:115]
	v_pk_add_f32 v[134:135], v[92:93], v[116:117]
	v_cvt_pk_bf16_f32 v116, v118, v119
	v_pk_add_f32 v[120:121], v[104:105], v[120:121]
	v_cvt_pk_bf16_f32 v118, v114, v115
	v_and_b32_e32 v115, 0xffff0000, v116
	v_cvt_pk_bf16_f32 v117, v120, v121
	v_lshlrev_b32_e32 v114, 16, v116
	v_mul_f32_e32 v115, v115, v115
	v_and_b32_e32 v121, 0xffff0000, v117
	v_fmac_f32_e32 v115, v114, v114
	v_lshlrev_b32_e32 v120, 16, v117
	v_add_f32_e32 v114, v115, v136
	v_mul_f32_e32 v115, v121, v121
	v_cvt_pk_bf16_f32 v119, v134, v135
	v_and_b32_e32 v135, 0xffff0000, v118
	v_fmac_f32_e32 v115, v120, v120
	v_lshlrev_b32_e32 v134, 16, v118
	v_add_f32_e32 v114, v115, v114
	v_mul_f32_e32 v115, v135, v135
	v_and_b32_e32 v142, 0xffff0000, v119
	v_fmac_f32_e32 v115, v134, v134
	v_lshlrev_b32_e32 v137, 16, v119
	v_add_f32_e32 v114, v115, v114
	v_mul_f32_e32 v115, v142, v142
	v_fmac_f32_e32 v115, v137, v137
	v_add_f32_e32 v114, v115, v114
	ds_bpermute_b32 v115, v249, v114
	v_lshlrev_b64 v[120:121], 11, v[210:211]
	v_lshl_add_u64 v[120:121], s[88:89], 0, v[120:121]
	v_lshl_add_u64 v[120:121], v[224:225], 1, v[120:121]
	global_store_dwordx4 v[120:121], v[126:129], off
	global_store_dwordx4 v[120:121], v[116:119], off offset:256
	s_waitcnt lgkmcnt(0)
	v_add_f32_e32 v114, v114, v115
	ds_bpermute_b32 v115, v248, v114
	s_and_saveexec_b64 s[42:43], vcc
	s_cbranch_execz .LBB0_835
	v_lshlrev_b64 v[116:117], 6, v[210:211]
	v_lshl_add_u64 v[116:117], s[68:69], 0, v[116:117]
	v_lshl_add_u64 v[116:117], s[10:11], 2, v[116:117]
	s_lshl_b32 s76, s54, 2
	v_lshl_add_u64 v[116:117], v[116:117], 0, s[76:77]
	s_waitcnt lgkmcnt(0)
	v_add_f32_e32 v114, v114, v115
	global_store_dword v[116:117], v114, off
.LBB0_835:
	s_or_b64 exec, exec, s[42:43]
	s_waitcnt vmcnt(17)
	v_lshlrev_b32_e32 v114, 16, v190
	s_waitcnt lgkmcnt(0)
	v_and_b32_e32 v115, 0xffff0000, v190
	v_pk_add_f32 v[110:111], v[110:111], v[114:115]
	v_lshlrev_b32_e32 v114, 16, v191
	v_and_b32_e32 v115, 0xffff0000, v191
	v_pk_add_f32 v[112:113], v[112:113], v[114:115]
	v_lshlrev_b32_e32 v114, 16, v192
	v_and_b32_e32 v115, 0xffff0000, v192
	v_pk_add_f32 v[98:99], v[98:99], v[114:115]
	v_pk_add_f32 v[110:111], v[106:107], v[110:111]
	v_pk_add_f32 v[114:115], v[94:95], v[98:99]
	v_lshlrev_b32_e32 v98, 16, v193
	v_and_b32_e32 v99, 0xffff0000, v193
	v_pk_add_f32 v[98:99], v[100:101], v[98:99]
	v_pk_add_f32 v[112:113], v[108:109], v[112:113]
	v_pk_add_f32 v[116:117], v[96:97], v[98:99]
	v_cvt_pk_bf16_f32 v98, v110, v111
	v_cvt_pk_bf16_f32 v99, v112, v113
	v_and_b32_e32 v111, 0xffff0000, v98
	v_lshlrev_b32_e32 v110, 16, v98
	v_and_b32_e32 v113, 0xffff0000, v99
	v_mul_f32_e32 v111, v111, v111
	v_cvt_pk_bf16_f32 v100, v114, v115
	v_lshlrev_b32_e32 v112, 16, v99
	v_fmac_f32_e32 v111, v110, v110
	v_mul_f32_e32 v110, v113, v113
	v_and_b32_e32 v115, 0xffff0000, v100
	v_fmac_f32_e32 v110, v112, v112
	v_cvt_pk_bf16_f32 v101, v116, v117
	v_lshlrev_b32_e32 v114, 16, v100
	v_add_f32_e32 v110, v111, v110
	v_mul_f32_e32 v111, v115, v115
	v_and_b32_e32 v117, 0xffff0000, v101
	v_fmac_f32_e32 v111, v114, v114
	v_lshlrev_b32_e32 v116, 16, v101
	v_add_f32_e32 v110, v111, v110
	v_mul_f32_e32 v111, v117, v117
	v_fmac_f32_e32 v111, v116, v116
	v_add_f32_e32 v112, v111, v110
	s_waitcnt vmcnt(16)
	v_lshlrev_b32_e32 v110, 16, v186
	v_and_b32_e32 v111, 0xffff0000, v186
	v_pk_add_f32 v[86:87], v[86:87], v[110:111]
	v_lshlrev_b32_e32 v110, 16, v187
	v_and_b32_e32 v111, 0xffff0000, v187
	v_pk_add_f32 v[88:89], v[88:89], v[110:111]
	v_lshlrev_b32_e32 v110, 16, v188
	v_and_b32_e32 v111, 0xffff0000, v188
	v_pk_add_f32 v[82:83], v[82:83], v[110:111]
	v_lshlrev_b32_e32 v110, 16, v189
	v_and_b32_e32 v111, 0xffff0000, v189
	v_pk_add_f32 v[86:87], v[102:103], v[86:87]
	v_pk_add_f32 v[84:85], v[84:85], v[110:111]
	v_pk_add_f32 v[82:83], v[90:91], v[82:83]
	v_pk_add_f32 v[110:111], v[92:93], v[84:85]
	v_cvt_pk_bf16_f32 v84, v86, v87
	v_pk_add_f32 v[88:89], v[104:105], v[88:89]
	v_cvt_pk_bf16_f32 v86, v82, v83
	v_and_b32_e32 v83, 0xffff0000, v84
	v_cvt_pk_bf16_f32 v85, v88, v89
	v_lshlrev_b32_e32 v82, 16, v84
	v_mul_f32_e32 v83, v83, v83
	v_and_b32_e32 v89, 0xffff0000, v85
	v_fmac_f32_e32 v83, v82, v82
	v_lshlrev_b32_e32 v88, 16, v85
	v_add_f32_e32 v82, v83, v112
	v_mul_f32_e32 v83, v89, v89
	v_cvt_pk_bf16_f32 v87, v110, v111
	v_and_b32_e32 v111, 0xffff0000, v86
	v_fmac_f32_e32 v83, v88, v88
	v_lshlrev_b32_e32 v110, 16, v86
	v_add_f32_e32 v82, v83, v82
	v_mul_f32_e32 v83, v111, v111
	v_and_b32_e32 v114, 0xffff0000, v87
	v_fmac_f32_e32 v83, v110, v110
	v_lshlrev_b32_e32 v113, 16, v87
	v_add_f32_e32 v82, v83, v82
	v_mul_f32_e32 v83, v114, v114
	v_fmac_f32_e32 v83, v113, v113
	v_add_f32_e32 v82, v83, v82
	ds_bpermute_b32 v83, v249, v82
	v_lshlrev_b64 v[88:89], 11, v[246:247]
	v_lshl_add_u64 v[88:89], s[88:89], 0, v[88:89]
	v_lshl_add_u64 v[88:89], v[224:225], 1, v[88:89]
	global_store_dwordx4 v[88:89], v[98:101], off
	global_store_dwordx4 v[88:89], v[84:87], off offset:256
	s_waitcnt lgkmcnt(0)
	v_add_f32_e32 v82, v82, v83
	ds_bpermute_b32 v83, v248, v82
	s_and_saveexec_b64 s[42:43], vcc
	s_cbranch_execz .LBB0_837
	v_lshlrev_b64 v[84:85], 6, v[246:247]
	v_lshl_add_u64 v[84:85], s[68:69], 0, v[84:85]
	v_lshl_add_u64 v[84:85], s[10:11], 2, v[84:85]
	s_lshl_b32 s76, s54, 2
	v_lshl_add_u64 v[84:85], v[84:85], 0, s[76:77]
	s_waitcnt lgkmcnt(0)
	v_add_f32_e32 v82, v82, v83
	global_store_dword v[84:85], v82, off
.LBB0_837:
	s_or_b64 exec, exec, s[42:43]
	s_waitcnt vmcnt(18)
	v_lshlrev_b32_e32 v82, 16, v182
	s_waitcnt lgkmcnt(0)
	v_and_b32_e32 v83, 0xffff0000, v182
	v_pk_add_f32 v[78:79], v[78:79], v[82:83]
	v_lshlrev_b32_e32 v82, 16, v183
	v_and_b32_e32 v83, 0xffff0000, v183
	v_pk_add_f32 v[80:81], v[80:81], v[82:83]
	v_lshlrev_b32_e32 v82, 16, v184
	v_and_b32_e32 v83, 0xffff0000, v184
	v_pk_add_f32 v[74:75], v[74:75], v[82:83]
	v_pk_add_f32 v[78:79], v[106:107], v[78:79]
	v_pk_add_f32 v[82:83], v[94:95], v[74:75]
	v_lshlrev_b32_e32 v74, 16, v185
	v_and_b32_e32 v75, 0xffff0000, v185
	v_pk_add_f32 v[74:75], v[76:77], v[74:75]
	v_pk_add_f32 v[80:81], v[108:109], v[80:81]
	v_pk_add_f32 v[84:85], v[96:97], v[74:75]
	v_cvt_pk_bf16_f32 v74, v78, v79
	v_cvt_pk_bf16_f32 v75, v80, v81
	v_and_b32_e32 v79, 0xffff0000, v74
	v_lshlrev_b32_e32 v78, 16, v74
	v_and_b32_e32 v81, 0xffff0000, v75
	v_mul_f32_e32 v79, v79, v79
	v_cvt_pk_bf16_f32 v76, v82, v83
	v_lshlrev_b32_e32 v80, 16, v75
	v_fmac_f32_e32 v79, v78, v78
	v_mul_f32_e32 v78, v81, v81
	v_and_b32_e32 v83, 0xffff0000, v76
	v_fmac_f32_e32 v78, v80, v80
	v_cvt_pk_bf16_f32 v77, v84, v85
	v_lshlrev_b32_e32 v82, 16, v76
	v_add_f32_e32 v78, v79, v78
	v_mul_f32_e32 v79, v83, v83
	v_and_b32_e32 v85, 0xffff0000, v77
	v_fmac_f32_e32 v79, v82, v82
	v_lshlrev_b32_e32 v84, 16, v77
	v_add_f32_e32 v78, v79, v78
	v_mul_f32_e32 v79, v85, v85
	v_fmac_f32_e32 v79, v84, v84
	v_add_f32_e32 v80, v79, v78
	s_waitcnt vmcnt(17)
	v_lshlrev_b32_e32 v78, 16, v178
	v_and_b32_e32 v79, 0xffff0000, v178
	v_pk_add_f32 v[70:71], v[70:71], v[78:79]
	v_lshlrev_b32_e32 v78, 16, v179
	v_and_b32_e32 v79, 0xffff0000, v179
	v_pk_add_f32 v[72:73], v[72:73], v[78:79]
	v_lshlrev_b32_e32 v78, 16, v180
	v_and_b32_e32 v79, 0xffff0000, v180
	v_pk_add_f32 v[66:67], v[66:67], v[78:79]
	v_lshlrev_b32_e32 v78, 16, v181
	v_and_b32_e32 v79, 0xffff0000, v181
	v_pk_add_f32 v[70:71], v[102:103], v[70:71]
	v_pk_add_f32 v[68:69], v[68:69], v[78:79]
	v_pk_add_f32 v[66:67], v[90:91], v[66:67]
	v_pk_add_f32 v[78:79], v[92:93], v[68:69]
	v_cvt_pk_bf16_f32 v68, v70, v71
	v_pk_add_f32 v[72:73], v[104:105], v[72:73]
	v_cvt_pk_bf16_f32 v70, v66, v67
	v_and_b32_e32 v67, 0xffff0000, v68
	v_cvt_pk_bf16_f32 v69, v72, v73
	v_lshlrev_b32_e32 v66, 16, v68
	v_mul_f32_e32 v67, v67, v67
	v_and_b32_e32 v73, 0xffff0000, v69
	v_fmac_f32_e32 v67, v66, v66
	v_lshlrev_b32_e32 v72, 16, v69
	v_add_f32_e32 v66, v67, v80
	v_mul_f32_e32 v67, v73, v73
	v_cvt_pk_bf16_f32 v71, v78, v79
	v_and_b32_e32 v79, 0xffff0000, v70
	v_fmac_f32_e32 v67, v72, v72
	v_lshlrev_b32_e32 v78, 16, v70
	v_add_f32_e32 v66, v67, v66
	v_mul_f32_e32 v67, v79, v79
	v_and_b32_e32 v82, 0xffff0000, v71
	v_fmac_f32_e32 v67, v78, v78
	v_lshlrev_b32_e32 v81, 16, v71
	v_add_f32_e32 v66, v67, v66
	v_mul_f32_e32 v67, v82, v82
	v_fmac_f32_e32 v67, v81, v81
	v_add_f32_e32 v66, v67, v66
	ds_bpermute_b32 v67, v249, v66
	v_lshlrev_b64 v[72:73], 11, v[242:243]
	v_lshl_add_u64 v[72:73], s[88:89], 0, v[72:73]
	v_lshl_add_u64 v[72:73], v[224:225], 1, v[72:73]
	global_store_dwordx4 v[72:73], v[74:77], off
	global_store_dwordx4 v[72:73], v[68:71], off offset:256
	s_waitcnt lgkmcnt(0)
	v_add_f32_e32 v66, v66, v67
	ds_bpermute_b32 v67, v248, v66
	s_and_saveexec_b64 s[42:43], vcc
	s_cbranch_execz .LBB0_839
	v_lshlrev_b64 v[68:69], 6, v[242:243]
	v_lshl_add_u64 v[68:69], s[68:69], 0, v[68:69]
	v_lshl_add_u64 v[68:69], s[10:11], 2, v[68:69]
	s_lshl_b32 s76, s54, 2
	v_lshl_add_u64 v[68:69], v[68:69], 0, s[76:77]
	s_waitcnt lgkmcnt(0)
	v_add_f32_e32 v66, v66, v67
	global_store_dword v[68:69], v66, off
.LBB0_839:
	s_or_b64 exec, exec, s[42:43]
	s_waitcnt vmcnt(19)
	v_lshlrev_b32_e32 v66, 16, v166
	s_waitcnt lgkmcnt(0)
	v_and_b32_e32 v67, 0xffff0000, v166
	v_pk_add_f32 v[62:63], v[62:63], v[66:67]
	v_lshlrev_b32_e32 v66, 16, v167
	v_and_b32_e32 v67, 0xffff0000, v167
	v_pk_add_f32 v[64:65], v[64:65], v[66:67]
	v_lshlrev_b32_e32 v66, 16, v168
	v_and_b32_e32 v67, 0xffff0000, v168
	v_pk_add_f32 v[58:59], v[58:59], v[66:67]
	v_pk_add_f32 v[62:63], v[106:107], v[62:63]
	v_pk_add_f32 v[66:67], v[94:95], v[58:59]
	v_lshlrev_b32_e32 v58, 16, v169
	v_and_b32_e32 v59, 0xffff0000, v169
	v_pk_add_f32 v[58:59], v[60:61], v[58:59]
	v_pk_add_f32 v[64:65], v[108:109], v[64:65]
	v_pk_add_f32 v[68:69], v[96:97], v[58:59]
	v_cvt_pk_bf16_f32 v58, v62, v63
	v_cvt_pk_bf16_f32 v59, v64, v65
	v_and_b32_e32 v63, 0xffff0000, v58
	v_lshlrev_b32_e32 v62, 16, v58
	v_and_b32_e32 v65, 0xffff0000, v59
	v_mul_f32_e32 v63, v63, v63
	v_cvt_pk_bf16_f32 v60, v66, v67
	v_lshlrev_b32_e32 v64, 16, v59
	v_fmac_f32_e32 v63, v62, v62
	v_mul_f32_e32 v62, v65, v65
	v_and_b32_e32 v67, 0xffff0000, v60
	v_fmac_f32_e32 v62, v64, v64
	v_cvt_pk_bf16_f32 v61, v68, v69
	v_lshlrev_b32_e32 v66, 16, v60
	v_add_f32_e32 v62, v63, v62
	v_mul_f32_e32 v63, v67, v67
	v_and_b32_e32 v69, 0xffff0000, v61
	v_fmac_f32_e32 v63, v66, v66
	v_lshlrev_b32_e32 v68, 16, v61
	v_add_f32_e32 v62, v63, v62
	v_mul_f32_e32 v63, v69, v69
	v_fmac_f32_e32 v63, v68, v68
	v_add_f32_e32 v64, v63, v62
	s_waitcnt vmcnt(18)
	v_lshlrev_b32_e32 v62, 16, v162
	v_and_b32_e32 v63, 0xffff0000, v162
	v_pk_add_f32 v[54:55], v[54:55], v[62:63]
	v_lshlrev_b32_e32 v62, 16, v163
	v_and_b32_e32 v63, 0xffff0000, v163
	v_pk_add_f32 v[56:57], v[56:57], v[62:63]
	v_lshlrev_b32_e32 v62, 16, v164
	v_and_b32_e32 v63, 0xffff0000, v164
	v_pk_add_f32 v[50:51], v[50:51], v[62:63]
	v_lshlrev_b32_e32 v62, 16, v165
	v_and_b32_e32 v63, 0xffff0000, v165
	v_pk_add_f32 v[54:55], v[102:103], v[54:55]
	v_pk_add_f32 v[52:53], v[52:53], v[62:63]
	v_pk_add_f32 v[50:51], v[90:91], v[50:51]
	v_pk_add_f32 v[62:63], v[92:93], v[52:53]
	v_cvt_pk_bf16_f32 v52, v54, v55
	v_pk_add_f32 v[56:57], v[104:105], v[56:57]
	v_cvt_pk_bf16_f32 v54, v50, v51
	v_and_b32_e32 v51, 0xffff0000, v52
	v_cvt_pk_bf16_f32 v53, v56, v57
	v_lshlrev_b32_e32 v50, 16, v52
	v_mul_f32_e32 v51, v51, v51
	v_and_b32_e32 v57, 0xffff0000, v53
	v_fmac_f32_e32 v51, v50, v50
	v_lshlrev_b32_e32 v56, 16, v53
	v_add_f32_e32 v50, v51, v64
	v_mul_f32_e32 v51, v57, v57
	v_cvt_pk_bf16_f32 v55, v62, v63
	v_and_b32_e32 v63, 0xffff0000, v54
	v_fmac_f32_e32 v51, v56, v56
	v_lshlrev_b32_e32 v62, 16, v54
	v_add_f32_e32 v50, v51, v50
	v_mul_f32_e32 v51, v63, v63
	v_and_b32_e32 v66, 0xffff0000, v55
	v_fmac_f32_e32 v51, v62, v62
	v_lshlrev_b32_e32 v65, 16, v55
	v_add_f32_e32 v50, v51, v50
	v_mul_f32_e32 v51, v66, v66
	v_fmac_f32_e32 v51, v65, v65
	v_add_f32_e32 v50, v51, v50
	ds_bpermute_b32 v51, v249, v50
	v_lshlrev_b64 v[56:57], 11, v[238:239]
	v_lshl_add_u64 v[56:57], s[88:89], 0, v[56:57]
	v_lshl_add_u64 v[56:57], v[224:225], 1, v[56:57]
	global_store_dwordx4 v[56:57], v[58:61], off
	global_store_dwordx4 v[56:57], v[52:55], off offset:256
	s_waitcnt lgkmcnt(0)
	v_add_f32_e32 v50, v50, v51
	ds_bpermute_b32 v51, v248, v50
	s_and_saveexec_b64 s[42:43], vcc
	s_cbranch_execz .LBB0_841
	v_lshlrev_b64 v[52:53], 6, v[238:239]
	v_lshl_add_u64 v[52:53], s[68:69], 0, v[52:53]
	v_lshl_add_u64 v[52:53], s[10:11], 2, v[52:53]
	s_lshl_b32 s76, s54, 2
	v_lshl_add_u64 v[52:53], v[52:53], 0, s[76:77]
	s_waitcnt lgkmcnt(0)
	v_add_f32_e32 v50, v50, v51
	global_store_dword v[52:53], v50, off
.LBB0_841:
	s_or_b64 exec, exec, s[42:43]
	s_waitcnt vmcnt(20)
	v_lshlrev_b32_e32 v50, 16, v158
	s_waitcnt lgkmcnt(0)
	v_and_b32_e32 v51, 0xffff0000, v158
	v_pk_add_f32 v[46:47], v[46:47], v[50:51]
	v_lshlrev_b32_e32 v50, 16, v159
	v_and_b32_e32 v51, 0xffff0000, v159
	v_pk_add_f32 v[48:49], v[48:49], v[50:51]
	v_lshlrev_b32_e32 v50, 16, v160
	v_and_b32_e32 v51, 0xffff0000, v160
	v_pk_add_f32 v[42:43], v[42:43], v[50:51]
	v_pk_add_f32 v[46:47], v[106:107], v[46:47]
	v_pk_add_f32 v[50:51], v[94:95], v[42:43]
	v_lshlrev_b32_e32 v42, 16, v161
	v_and_b32_e32 v43, 0xffff0000, v161
	v_pk_add_f32 v[42:43], v[44:45], v[42:43]
	v_pk_add_f32 v[48:49], v[108:109], v[48:49]
	v_pk_add_f32 v[52:53], v[96:97], v[42:43]
	v_cvt_pk_bf16_f32 v42, v46, v47
	v_cvt_pk_bf16_f32 v43, v48, v49
	v_and_b32_e32 v47, 0xffff0000, v42
	v_lshlrev_b32_e32 v46, 16, v42
	v_and_b32_e32 v49, 0xffff0000, v43
	v_mul_f32_e32 v47, v47, v47
	v_cvt_pk_bf16_f32 v44, v50, v51
	v_lshlrev_b32_e32 v48, 16, v43
	v_fmac_f32_e32 v47, v46, v46
	v_mul_f32_e32 v46, v49, v49
	v_and_b32_e32 v51, 0xffff0000, v44
	v_fmac_f32_e32 v46, v48, v48
	v_cvt_pk_bf16_f32 v45, v52, v53
	v_lshlrev_b32_e32 v50, 16, v44
	v_add_f32_e32 v46, v47, v46
	v_mul_f32_e32 v47, v51, v51
	v_and_b32_e32 v53, 0xffff0000, v45
	v_fmac_f32_e32 v47, v50, v50
	v_lshlrev_b32_e32 v52, 16, v45
	v_add_f32_e32 v46, v47, v46
	v_mul_f32_e32 v47, v53, v53
	v_fmac_f32_e32 v47, v52, v52
	v_add_f32_e32 v48, v47, v46
	s_waitcnt vmcnt(19)
	v_lshlrev_b32_e32 v46, 16, v154
	v_and_b32_e32 v47, 0xffff0000, v154
	v_pk_add_f32 v[38:39], v[38:39], v[46:47]
	v_lshlrev_b32_e32 v46, 16, v155
	v_and_b32_e32 v47, 0xffff0000, v155
	v_pk_add_f32 v[40:41], v[40:41], v[46:47]
	v_lshlrev_b32_e32 v46, 16, v156
	v_and_b32_e32 v47, 0xffff0000, v156
	v_pk_add_f32 v[34:35], v[34:35], v[46:47]
	v_lshlrev_b32_e32 v46, 16, v157
	v_and_b32_e32 v47, 0xffff0000, v157
	v_pk_add_f32 v[38:39], v[102:103], v[38:39]
	v_pk_add_f32 v[36:37], v[36:37], v[46:47]
	v_pk_add_f32 v[34:35], v[90:91], v[34:35]
	v_pk_add_f32 v[46:47], v[92:93], v[36:37]
	v_cvt_pk_bf16_f32 v36, v38, v39
	v_pk_add_f32 v[40:41], v[104:105], v[40:41]
	v_cvt_pk_bf16_f32 v38, v34, v35
	v_and_b32_e32 v35, 0xffff0000, v36
	v_cvt_pk_bf16_f32 v37, v40, v41
	v_lshlrev_b32_e32 v34, 16, v36
	v_mul_f32_e32 v35, v35, v35
	v_and_b32_e32 v41, 0xffff0000, v37
	v_fmac_f32_e32 v35, v34, v34
	v_lshlrev_b32_e32 v40, 16, v37
	v_add_f32_e32 v34, v35, v48
	v_mul_f32_e32 v35, v41, v41
	v_cvt_pk_bf16_f32 v39, v46, v47
	v_and_b32_e32 v47, 0xffff0000, v38
	v_fmac_f32_e32 v35, v40, v40
	v_lshlrev_b32_e32 v46, 16, v38
	v_add_f32_e32 v34, v35, v34
	v_mul_f32_e32 v35, v47, v47
	v_and_b32_e32 v50, 0xffff0000, v39
	v_fmac_f32_e32 v35, v46, v46
	v_lshlrev_b32_e32 v49, 16, v39
	v_add_f32_e32 v34, v35, v34
	v_mul_f32_e32 v35, v50, v50
	v_fmac_f32_e32 v35, v49, v49
	v_add_f32_e32 v34, v35, v34
	ds_bpermute_b32 v35, v249, v34
	v_lshlrev_b64 v[40:41], 11, v[234:235]
	v_lshl_add_u64 v[40:41], s[88:89], 0, v[40:41]
	v_lshl_add_u64 v[40:41], v[224:225], 1, v[40:41]
	global_store_dwordx4 v[40:41], v[42:45], off
	global_store_dwordx4 v[40:41], v[36:39], off offset:256
	s_waitcnt lgkmcnt(0)
	v_add_f32_e32 v34, v34, v35
	ds_bpermute_b32 v35, v248, v34
	s_and_saveexec_b64 s[42:43], vcc
	s_cbranch_execz .LBB0_843
	v_lshlrev_b64 v[36:37], 6, v[234:235]
	v_lshl_add_u64 v[36:37], s[68:69], 0, v[36:37]
	v_lshl_add_u64 v[36:37], s[10:11], 2, v[36:37]
	s_lshl_b32 s76, s54, 2
	v_lshl_add_u64 v[36:37], v[36:37], 0, s[76:77]
	s_waitcnt lgkmcnt(0)
	v_add_f32_e32 v34, v34, v35
	global_store_dword v[36:37], v34, off
.LBB0_843:
	s_or_b64 exec, exec, s[42:43]
	s_waitcnt vmcnt(21)
	v_lshlrev_b32_e32 v34, 16, v150
	s_waitcnt lgkmcnt(0)
	v_and_b32_e32 v35, 0xffff0000, v150
	v_pk_add_f32 v[30:31], v[30:31], v[34:35]
	v_lshlrev_b32_e32 v34, 16, v151
	v_and_b32_e32 v35, 0xffff0000, v151
	v_pk_add_f32 v[32:33], v[32:33], v[34:35]
	v_lshlrev_b32_e32 v34, 16, v152
	v_and_b32_e32 v35, 0xffff0000, v152
	v_pk_add_f32 v[26:27], v[26:27], v[34:35]
	v_pk_add_f32 v[30:31], v[106:107], v[30:31]
	v_pk_add_f32 v[34:35], v[94:95], v[26:27]
	v_lshlrev_b32_e32 v26, 16, v153
	v_and_b32_e32 v27, 0xffff0000, v153
	v_pk_add_f32 v[26:27], v[28:29], v[26:27]
	v_pk_add_f32 v[32:33], v[108:109], v[32:33]
	v_pk_add_f32 v[36:37], v[96:97], v[26:27]
	v_cvt_pk_bf16_f32 v26, v30, v31
	v_cvt_pk_bf16_f32 v27, v32, v33
	v_and_b32_e32 v31, 0xffff0000, v26
	v_lshlrev_b32_e32 v30, 16, v26
	v_and_b32_e32 v33, 0xffff0000, v27
	v_mul_f32_e32 v31, v31, v31
	v_cvt_pk_bf16_f32 v28, v34, v35
	v_lshlrev_b32_e32 v32, 16, v27
	v_fmac_f32_e32 v31, v30, v30
	v_mul_f32_e32 v30, v33, v33
	v_and_b32_e32 v35, 0xffff0000, v28
	v_fmac_f32_e32 v30, v32, v32
	v_cvt_pk_bf16_f32 v29, v36, v37
	v_lshlrev_b32_e32 v34, 16, v28
	v_add_f32_e32 v30, v31, v30
	v_mul_f32_e32 v31, v35, v35
	v_and_b32_e32 v37, 0xffff0000, v29
	v_fmac_f32_e32 v31, v34, v34
	v_lshlrev_b32_e32 v36, 16, v29
	v_add_f32_e32 v30, v31, v30
	v_mul_f32_e32 v31, v37, v37
	v_fmac_f32_e32 v31, v36, v36
	v_add_f32_e32 v32, v31, v30
	s_waitcnt vmcnt(20)
	v_lshlrev_b32_e32 v30, 16, v138
	v_and_b32_e32 v31, 0xffff0000, v138
	v_pk_add_f32 v[22:23], v[22:23], v[30:31]
	v_lshlrev_b32_e32 v30, 16, v139
	v_and_b32_e32 v31, 0xffff0000, v139
	v_pk_add_f32 v[24:25], v[24:25], v[30:31]
	v_lshlrev_b32_e32 v30, 16, v140
	v_and_b32_e32 v31, 0xffff0000, v140
	v_pk_add_f32 v[18:19], v[18:19], v[30:31]
	v_lshlrev_b32_e32 v30, 16, v141
	v_and_b32_e32 v31, 0xffff0000, v141
	v_pk_add_f32 v[22:23], v[102:103], v[22:23]
	v_pk_add_f32 v[20:21], v[20:21], v[30:31]
	v_pk_add_f32 v[18:19], v[90:91], v[18:19]
	v_pk_add_f32 v[30:31], v[92:93], v[20:21]
	v_cvt_pk_bf16_f32 v20, v22, v23
	v_pk_add_f32 v[24:25], v[104:105], v[24:25]
	v_cvt_pk_bf16_f32 v22, v18, v19
	v_and_b32_e32 v19, 0xffff0000, v20
	v_cvt_pk_bf16_f32 v21, v24, v25
	v_lshlrev_b32_e32 v18, 16, v20
	v_mul_f32_e32 v19, v19, v19
	v_and_b32_e32 v25, 0xffff0000, v21
	v_fmac_f32_e32 v19, v18, v18
	v_lshlrev_b32_e32 v24, 16, v21
	v_add_f32_e32 v18, v19, v32
	v_mul_f32_e32 v19, v25, v25
	v_cvt_pk_bf16_f32 v23, v30, v31
	v_and_b32_e32 v31, 0xffff0000, v22
	v_fmac_f32_e32 v19, v24, v24
	v_lshlrev_b32_e32 v30, 16, v22
	v_add_f32_e32 v18, v19, v18
	v_mul_f32_e32 v19, v31, v31
	v_and_b32_e32 v34, 0xffff0000, v23
	v_fmac_f32_e32 v19, v30, v30
	v_lshlrev_b32_e32 v33, 16, v23
	v_add_f32_e32 v18, v19, v18
	v_mul_f32_e32 v19, v34, v34
	v_fmac_f32_e32 v19, v33, v33
	v_add_f32_e32 v18, v19, v18
	ds_bpermute_b32 v19, v249, v18
	v_lshlrev_b64 v[24:25], 11, v[230:231]
	v_lshl_add_u64 v[24:25], s[88:89], 0, v[24:25]
	v_lshl_add_u64 v[24:25], v[224:225], 1, v[24:25]
	global_store_dwordx4 v[24:25], v[26:29], off
	global_store_dwordx4 v[24:25], v[20:23], off offset:256
	s_waitcnt lgkmcnt(0)
	v_add_f32_e32 v18, v18, v19
	ds_bpermute_b32 v19, v248, v18
	s_and_saveexec_b64 s[42:43], vcc
	s_cbranch_execz .LBB0_845
	v_lshlrev_b64 v[20:21], 6, v[230:231]
	v_lshl_add_u64 v[20:21], s[68:69], 0, v[20:21]
	v_lshl_add_u64 v[20:21], s[10:11], 2, v[20:21]
	s_lshl_b32 s76, s54, 2
	v_lshl_add_u64 v[20:21], v[20:21], 0, s[76:77]
	s_waitcnt lgkmcnt(0)
	v_add_f32_e32 v18, v18, v19
	global_store_dword v[20:21], v18, off
.LBB0_845:
	s_or_b64 exec, exec, s[42:43]
	s_waitcnt vmcnt(22)
	v_lshlrev_b32_e32 v18, 16, v130
	s_waitcnt lgkmcnt(0)
	v_and_b32_e32 v19, 0xffff0000, v130
	v_pk_add_f32 v[14:15], v[14:15], v[18:19]
	v_lshlrev_b32_e32 v18, 16, v131
	v_and_b32_e32 v19, 0xffff0000, v131
	v_pk_add_f32 v[16:17], v[16:17], v[18:19]
	v_lshlrev_b32_e32 v18, 16, v132
	v_and_b32_e32 v19, 0xffff0000, v132
	v_pk_add_f32 v[10:11], v[10:11], v[18:19]
	v_pk_add_f32 v[14:15], v[106:107], v[14:15]
	v_pk_add_f32 v[18:19], v[94:95], v[10:11]
	v_lshlrev_b32_e32 v10, 16, v133
	v_and_b32_e32 v11, 0xffff0000, v133
	v_pk_add_f32 v[10:11], v[12:13], v[10:11]
	v_pk_add_f32 v[16:17], v[108:109], v[16:17]
	v_pk_add_f32 v[20:21], v[96:97], v[10:11]
	v_cvt_pk_bf16_f32 v10, v14, v15
	v_cvt_pk_bf16_f32 v11, v16, v17
	v_and_b32_e32 v15, 0xffff0000, v10
	v_lshlrev_b32_e32 v14, 16, v10
	v_and_b32_e32 v17, 0xffff0000, v11
	v_mul_f32_e32 v15, v15, v15
	v_cvt_pk_bf16_f32 v12, v18, v19
	v_lshlrev_b32_e32 v16, 16, v11
	v_fmac_f32_e32 v15, v14, v14
	v_mul_f32_e32 v14, v17, v17
	v_and_b32_e32 v19, 0xffff0000, v12
	v_fmac_f32_e32 v14, v16, v16
	v_cvt_pk_bf16_f32 v13, v20, v21
	v_lshlrev_b32_e32 v18, 16, v12
	v_add_f32_e32 v14, v15, v14
	v_mul_f32_e32 v15, v19, v19
	v_and_b32_e32 v21, 0xffff0000, v13
	v_fmac_f32_e32 v15, v18, v18
	v_lshlrev_b32_e32 v20, 16, v13
	v_add_f32_e32 v14, v15, v14
	v_mul_f32_e32 v15, v21, v21
	v_fmac_f32_e32 v15, v20, v20
	v_add_f32_e32 v16, v15, v14
	s_waitcnt vmcnt(21)
	v_lshlrev_b32_e32 v14, 16, v122
	v_and_b32_e32 v15, 0xffff0000, v122
	v_pk_add_f32 v[6:7], v[6:7], v[14:15]
	v_lshlrev_b32_e32 v14, 16, v123
	v_and_b32_e32 v15, 0xffff0000, v123
	v_pk_add_f32 v[8:9], v[8:9], v[14:15]
	v_lshlrev_b32_e32 v14, 16, v124
	v_and_b32_e32 v15, 0xffff0000, v124
	v_pk_add_f32 v[2:3], v[2:3], v[14:15]
	v_lshlrev_b32_e32 v14, 16, v125
	v_and_b32_e32 v15, 0xffff0000, v125
	v_pk_add_f32 v[6:7], v[102:103], v[6:7]
	v_pk_add_f32 v[4:5], v[4:5], v[14:15]
	v_pk_add_f32 v[2:3], v[90:91], v[2:3]
	v_pk_add_f32 v[14:15], v[92:93], v[4:5]
	v_cvt_pk_bf16_f32 v4, v6, v7
	v_pk_add_f32 v[8:9], v[104:105], v[8:9]
	v_cvt_pk_bf16_f32 v6, v2, v3
	v_and_b32_e32 v3, 0xffff0000, v4
	v_cvt_pk_bf16_f32 v5, v8, v9
	v_lshlrev_b32_e32 v2, 16, v4
	v_mul_f32_e32 v3, v3, v3
	v_and_b32_e32 v9, 0xffff0000, v5
	v_fmac_f32_e32 v3, v2, v2
	v_lshlrev_b32_e32 v8, 16, v5
	v_add_f32_e32 v2, v3, v16
	v_mul_f32_e32 v3, v9, v9
	v_cvt_pk_bf16_f32 v7, v14, v15
	v_and_b32_e32 v15, 0xffff0000, v6
	v_fmac_f32_e32 v3, v8, v8
	v_lshlrev_b32_e32 v14, 16, v6
	v_add_f32_e32 v2, v3, v2
	v_mul_f32_e32 v3, v15, v15
	v_and_b32_e32 v18, 0xffff0000, v7
	v_fmac_f32_e32 v3, v14, v14
	v_lshlrev_b32_e32 v17, 16, v7
	v_add_f32_e32 v2, v3, v2
	v_mul_f32_e32 v3, v18, v18
	v_fmac_f32_e32 v3, v17, v17
	v_add_f32_e32 v2, v3, v2
	ds_bpermute_b32 v3, v249, v2
	v_lshlrev_b64 v[8:9], 11, v[226:227]
	v_lshl_add_u64 v[8:9], s[88:89], 0, v[8:9]
	v_lshl_add_u64 v[8:9], v[224:225], 1, v[8:9]
	global_store_dwordx4 v[8:9], v[10:13], off
	global_store_dwordx4 v[8:9], v[4:7], off offset:256
	s_waitcnt lgkmcnt(0)
	v_add_f32_e32 v2, v2, v3
	ds_bpermute_b32 v3, v248, v2
	s_and_saveexec_b64 s[42:43], vcc
	s_cbranch_execz .LBB0_847
	v_lshlrev_b64 v[4:5], 6, v[226:227]
	v_lshl_add_u64 v[4:5], s[68:69], 0, v[4:5]
	v_lshl_add_u64 v[4:5], s[10:11], 2, v[4:5]
	s_lshl_b32 s76, s54, 2
	v_lshl_add_u64 v[4:5], v[4:5], 0, s[76:77]
	s_waitcnt lgkmcnt(0)
	v_add_f32_e32 v2, v2, v3
	global_store_dword v[4:5], v2, off
